# v19 minus the back-to-back s_setprio 0 / s_setprio 1 pair between the two MFMA blocks of each phase (28 sites)
# baseline (speedup 1.0000x reference)
; #define PG8_STAGE(bufoff, gbase, voff) do { _Pragma("unroll") for (int _i = 0; _i < 2; ++_i) \
;         __builtin_amdgcn_global_load_lds((const unsigned*)((const char*)(gbase) + (voff)[_i]), (PG8_LAS unsigned*)(lds + (bufoff) + ldsw + _i * 8192), 16, 0, 0); } while (0)
; #define PG8_LDA(dst, b, h) do { _Pragma("unroll") for (int m = 0; m < 4; ++m) _Pragma("unroll") for (int k = 0; k < 2; ++k) dst[m][k] = *(const PG8_LAS bf16x8*)(lds + PG8_SA(b, h) + aoff + m * 2048 + k * 1024); } while (0)
; #define PG8_LDB(dst, b, h) do { _Pragma("unroll") for (int n = 0; n < 2; ++n) _Pragma("unroll") for (int k = 0; k < 2; ++k) dst[n][k] = *(const PG8_LAS bf16x8*)(lds + PG8_SB(b, h) + boff + n * 2048 + k * 1024); } while (0)
; #define PG8_MMA(ai, bj, At, Bt) do { __builtin_amdgcn_s_setprio(1); _Pragma("unroll") for (int m = 0; m < 4; ++m) _Pragma("unroll") for (int n = 0; n < 2; ++n) _Pragma("unroll") for (int k = 0; k < 2; ++k) \
;         acc[ai][bj][m][n] = __builtin_amdgcn_mfma_f32_16x16x32_bf16(Bt[n][k], At[m][k], acc[ai][bj][m][n], 0, 0, 0); __builtin_amdgcn_s_setprio(0); } while (0)
; #define PG8_WAIT_V(n) asm volatile("s_waitcnt vmcnt(" #n ")" ::: "memory")
; #define PG8_WAIT_L(n) asm volatile("s_waitcnt lgkmcnt(" #n ")" ::: "memory")
; #define PG8_BAR __builtin_amdgcn_s_barrier()
; #define PG8_SCHED __builtin_amdgcn_sched_barrier(0)
; template <class Epi, class Sched, bool ALIGN_EPI = false, bool SP2 = false>
; __device__ __forceinline__ void gemm_phase(PG8_LAS unsigned char* lds, const Gemm g, const Sched& S, const Epi& E) {
;     ...
;             PG8_LDB(B0, 0, 0); PG8_LDB(B1, 0, 1); PG8_SCHED; PG8_LDA(At, 0, 0); PG8_STAGE(PG8_SA(1, 1), a1 + hstep, voffA);
;             PG8_WAIT_V(8); PG8_WAIT_L(0); PG8_BAR; PG8_MMA(0, 0, At, B0); PG8_MMA(0, 1, At, B1); PG8_BAR; PG8_SCHED;
;             PG8_LDA(At, 0, 1); PG8_STAGE(PG8_SB(0, 0), b2, voffB); PG8_STAGE(PG8_SB(0, 1), b2 + hstep, voffB); PG8_STAGE(PG8_SA(0, 0), a2, voffA);
;             PG8_WAIT_V(8); PG8_WAIT_L(0); PG8_BAR; PG8_MMA(1, 0, At, B0); PG8_MMA(1, 1, At, B1); PG8_BAR; PG8_SCHED;
.Lrj_P1_0:
	s_waitcnt lgkmcnt(0)
	s_barrier
	s_setprio 1
	s_waitcnt lgkmcnt(0)
	v_mfma_f32_16x16x32_bf16 v[124:127], v[128:131], v[202:205], v[124:127]
	v_mfma_f32_16x16x32_bf16 v[120:123], v[136:139], v[202:205], v[120:123]
	v_mfma_f32_16x16x32_bf16 v[108:111], v[128:131], v[210:213], v[108:111]
	v_mfma_f32_16x16x32_bf16 v[104:107], v[136:139], v[210:213], v[104:107]
	v_mfma_f32_16x16x32_bf16 v[92:95], v[128:131], v[218:221], v[92:95]
	v_mfma_f32_16x16x32_bf16 v[88:91], v[136:139], v[218:221], v[88:91]
	v_mfma_f32_16x16x32_bf16 v[76:79], v[128:131], v[230:233], v[76:79]
	v_mfma_f32_16x16x32_bf16 v[72:75], v[136:139], v[230:233], v[72:75]
	v_mfma_f32_16x16x32_bf16 v[124:127], v[132:135], v[206:209], v[124:127]
	v_mfma_f32_16x16x32_bf16 v[120:123], v[140:143], v[206:209], v[120:123]
	v_mfma_f32_16x16x32_bf16 v[108:111], v[132:135], v[214:217], v[108:111]
	v_mfma_f32_16x16x32_bf16 v[104:107], v[140:143], v[214:217], v[104:107]
	v_mfma_f32_16x16x32_bf16 v[92:95], v[132:135], v[222:225], v[92:95]
	v_mfma_f32_16x16x32_bf16 v[88:91], v[140:143], v[222:225], v[88:91]
	v_mfma_f32_16x16x32_bf16 v[76:79], v[132:135], v[234:237], v[76:79]
	v_mfma_f32_16x16x32_bf16 v[72:75], v[140:143], v[234:237], v[72:75]
	v_mfma_f32_16x16x32_bf16 v[116:119], v[144:147], v[202:205], v[116:119]
	v_mfma_f32_16x16x32_bf16 v[112:115], v[184:187], v[202:205], v[112:115]
	v_mfma_f32_16x16x32_bf16 v[100:103], v[144:147], v[210:213], v[100:103]
	v_mfma_f32_16x16x32_bf16 v[96:99], v[184:187], v[210:213], v[96:99]
	v_mfma_f32_16x16x32_bf16 v[84:87], v[144:147], v[218:221], v[84:87]
	v_mfma_f32_16x16x32_bf16 v[80:83], v[184:187], v[218:221], v[80:83]
	v_mfma_f32_16x16x32_bf16 v[68:71], v[144:147], v[230:233], v[68:71]
	v_mfma_f32_16x16x32_bf16 v[64:67], v[184:187], v[230:233], v[64:67]
	v_mfma_f32_16x16x32_bf16 v[116:119], v[148:151], v[206:209], v[116:119]
	v_mfma_f32_16x16x32_bf16 v[112:115], v[188:191], v[206:209], v[112:115]
	v_mfma_f32_16x16x32_bf16 v[100:103], v[148:151], v[214:217], v[100:103]
	v_mfma_f32_16x16x32_bf16 v[96:99], v[188:191], v[214:217], v[96:99]
	v_mfma_f32_16x16x32_bf16 v[84:87], v[148:151], v[222:225], v[84:87]
	v_mfma_f32_16x16x32_bf16 v[80:83], v[188:191], v[222:225], v[80:83]
	v_mfma_f32_16x16x32_bf16 v[68:71], v[148:151], v[234:237], v[68:71]
	v_mfma_f32_16x16x32_bf16 v[64:67], v[188:191], v[234:237], v[64:67]
	s_setprio 0
	s_barrier
	s_add_i32 s29, s33, s74
	v_lshl_add_u64 v[192:193], s[6:7], 0, v[158:159]
	s_mov_b32 m0, s29
	ds_read_b128 v[202:205], v194 offset:16384
	ds_read_b128 v[206:209], v194 offset:17408
	ds_read_b128 v[210:213], v194 offset:18432
	ds_read_b128 v[214:217], v194 offset:19456
	ds_read_b128 v[218:221], v194 offset:20480
	ds_read_b128 v[222:225], v194 offset:21504
	ds_read_b128 v[230:233], v194 offset:22528
	ds_read_b128 v[234:237], v194 offset:23552
	global_load_lds_dwordx4 v[192:193], off
	s_add_i32 m0, s29, 0x2000
	s_add_u32 s38, s6, 0x40000
	v_lshl_add_u64 v[238:239], s[6:7], 0, v[162:163]
	s_addc_u32 s39, s7, 0
	s_add_i32 s29, s83, s74
	global_load_lds_dwordx4 v[238:239], off
	v_lshl_add_u64 v[240:241], s[38:39], 0, v[158:159]
	s_mov_b32 m0, s29
	v_lshl_add_u64 v[242:243], s[8:9], 0, v[160:161]
	global_load_lds_dwordx4 v[240:241], off
	v_lshl_add_u64 v[240:241], s[38:39], 0, v[162:163]
	s_add_i32 m0, s29, 0x2000
	s_nop 0
	global_load_lds_dwordx4 v[240:241], off
	v_lshl_add_u64 v[240:241], s[8:9], 0, v[156:157]
	s_mov_b32 m0, s37
	s_nop 0
	global_load_lds_dwordx4 v[240:241], off
	s_mov_b32 m0, s75
	s_nop 0
	global_load_lds_dwordx4 v[242:243], off
	s_cmp_eq_u32 s99, 1
	s_cbranch_scc1 .Lrw_P1_1
	s_waitcnt vmcnt(8)
	s_branch .Lrj_P1_1

; #define PG8_STAGE(bufoff, gbase, voff) do { _Pragma("unroll") for (int _i = 0; _i < 2; ++_i) \
;         __builtin_amdgcn_global_load_lds((const unsigned*)((const char*)(gbase) + (voff)[_i]), (PG8_LAS unsigned*)(lds + (bufoff) + ldsw + _i * 8192), 16, 0, 0); } while (0)
; #define PG8_LDA(dst, b, h) do { _Pragma("unroll") for (int m = 0; m < 4; ++m) _Pragma("unroll") for (int k = 0; k < 2; ++k) dst[m][k] = *(const PG8_LAS bf16x8*)(lds + PG8_SA(b, h) + aoff + m * 2048 + k * 1024); } while (0)
; #define PG8_LDB(dst, b, h) do { _Pragma("unroll") for (int n = 0; n < 2; ++n) _Pragma("unroll") for (int k = 0; k < 2; ++k) dst[n][k] = *(const PG8_LAS bf16x8*)(lds + PG8_SB(b, h) + boff + n * 2048 + k * 1024); } while (0)
; #define PG8_MMA(ai, bj, At, Bt) do { __builtin_amdgcn_s_setprio(1); _Pragma("unroll") for (int m = 0; m < 4; ++m) _Pragma("unroll") for (int n = 0; n < 2; ++n) _Pragma("unroll") for (int k = 0; k < 2; ++k) \
;         acc[ai][bj][m][n] = __builtin_amdgcn_mfma_f32_16x16x32_bf16(Bt[n][k], At[m][k], acc[ai][bj][m][n], 0, 0, 0); __builtin_amdgcn_s_setprio(0); } while (0)
; #define PG8_WAIT_V(n) asm volatile("s_waitcnt vmcnt(" #n ")" ::: "memory")
; #define PG8_WAIT_L(n) asm volatile("s_waitcnt lgkmcnt(" #n ")" ::: "memory")
; #define PG8_BAR __builtin_amdgcn_s_barrier()
; #define PG8_SCHED __builtin_amdgcn_sched_barrier(0)
; template <class Epi, class Sched, bool ALIGN_EPI = false, bool SP2 = false>
; __device__ __forceinline__ void gemm_phase(PG8_LAS unsigned char* lds, const Gemm g, const Sched& S, const Epi& E) {
;     ...
;             PG8_WAIT_V(8); PG8_WAIT_L(0); PG8_BAR; PG8_MMA(1, 0, At, B0); PG8_MMA(1, 1, At, B1); PG8_BAR; PG8_SCHED;
;             PG8_LDB(B0, 1, 0); PG8_LDB(B1, 1, 1); PG8_SCHED; PG8_LDA(At, 1, 0); PG8_STAGE(PG8_SA(0, 1), a2 + hstep, voffA);
;             PG8_WAIT_V(8); PG8_WAIT_L(0); PG8_BAR; PG8_MMA(0, 0, At, B0); PG8_MMA(0, 1, At, B1); PG8_BAR; PG8_SCHED;
.Lrj_P1_1:
	s_waitcnt lgkmcnt(0)
	s_barrier
	s_setprio 1
	s_waitcnt lgkmcnt(0)
	v_mfma_f32_16x16x32_bf16 v[60:63], v[128:131], v[202:205], v[60:63]
	v_mfma_f32_16x16x32_bf16 v[56:59], v[136:139], v[202:205], v[56:59]
	v_mfma_f32_16x16x32_bf16 v[44:47], v[128:131], v[210:213], v[44:47]
	v_mfma_f32_16x16x32_bf16 v[40:43], v[136:139], v[210:213], v[40:43]
	v_mfma_f32_16x16x32_bf16 v[28:31], v[128:131], v[218:221], v[28:31]
	v_mfma_f32_16x16x32_bf16 v[24:27], v[136:139], v[218:221], v[24:27]
	v_mfma_f32_16x16x32_bf16 v[12:15], v[128:131], v[230:233], v[12:15]
	v_mfma_f32_16x16x32_bf16 v[8:11], v[136:139], v[230:233], v[8:11]
	v_mfma_f32_16x16x32_bf16 v[60:63], v[132:135], v[206:209], v[60:63]
	v_mfma_f32_16x16x32_bf16 v[56:59], v[140:143], v[206:209], v[56:59]
	v_mfma_f32_16x16x32_bf16 v[44:47], v[132:135], v[214:217], v[44:47]
	v_mfma_f32_16x16x32_bf16 v[40:43], v[140:143], v[214:217], v[40:43]
	v_mfma_f32_16x16x32_bf16 v[28:31], v[132:135], v[222:225], v[28:31]
	v_mfma_f32_16x16x32_bf16 v[24:27], v[140:143], v[222:225], v[24:27]
	v_mfma_f32_16x16x32_bf16 v[12:15], v[132:135], v[234:237], v[12:15]
	v_mfma_f32_16x16x32_bf16 v[8:11], v[140:143], v[234:237], v[8:11]
	v_mfma_f32_16x16x32_bf16 v[52:55], v[144:147], v[202:205], v[52:55]
	v_mfma_f32_16x16x32_bf16 v[48:51], v[184:187], v[202:205], v[48:51]
	v_mfma_f32_16x16x32_bf16 v[36:39], v[144:147], v[210:213], v[36:39]
	v_mfma_f32_16x16x32_bf16 v[32:35], v[184:187], v[210:213], v[32:35]
	v_mfma_f32_16x16x32_bf16 v[20:23], v[144:147], v[218:221], v[20:23]
	v_mfma_f32_16x16x32_bf16 v[16:19], v[184:187], v[218:221], v[16:19]
	v_mfma_f32_16x16x32_bf16 v[4:7], v[144:147], v[230:233], v[4:7]
	v_mfma_f32_16x16x32_bf16 v[0:3], v[184:187], v[230:233], v[0:3]
	v_mfma_f32_16x16x32_bf16 v[52:55], v[148:151], v[206:209], v[52:55]
	v_mfma_f32_16x16x32_bf16 v[48:51], v[188:191], v[206:209], v[48:51]
	v_mfma_f32_16x16x32_bf16 v[36:39], v[148:151], v[214:217], v[36:39]
	v_mfma_f32_16x16x32_bf16 v[32:35], v[188:191], v[214:217], v[32:35]
	v_mfma_f32_16x16x32_bf16 v[20:23], v[148:151], v[222:225], v[20:23]
	v_mfma_f32_16x16x32_bf16 v[16:19], v[188:191], v[222:225], v[16:19]
	v_mfma_f32_16x16x32_bf16 v[4:7], v[148:151], v[234:237], v[4:7]
	v_mfma_f32_16x16x32_bf16 v[0:3], v[188:191], v[234:237], v[0:3]
	s_setprio 0
	s_barrier
	s_add_i32 s29, 0, 0x18000
	s_add_i32 s38, 0, 0x1c000
	v_add_u32_e32 v140, s29, v169
	v_add_u32_e32 v164, s38, v169
	ds_read_b128 v[128:131], v140
	ds_read_b128 v[132:135], v140 offset:1024
	ds_read_b128 v[136:139], v140 offset:2048
	ds_read_b128 v[140:143], v140 offset:3072
	ds_read_b128 v[144:147], v164
	ds_read_b128 v[148:151], v164 offset:1024
	ds_read_b128 v[184:187], v164 offset:2048
	ds_read_b128 v[188:191], v164 offset:3072
	s_add_u32 s8, s8, 0x40000
	s_addc_u32 s9, s9, 0
	s_mov_b32 m0, s76
	v_lshl_add_u64 v[244:245], s[8:9], 0, v[156:157]
	ds_read_b128 v[202:205], v194 offset:32768
	ds_read_b128 v[206:209], v194 offset:33792
	ds_read_b128 v[210:213], v194 offset:34816
	ds_read_b128 v[214:217], v194 offset:35840
	ds_read_b128 v[218:221], v194 offset:36864
	ds_read_b128 v[222:225], v194 offset:37888
	ds_read_b128 v[230:233], v194 offset:38912
	ds_read_b128 v[234:237], v194 offset:39936
	global_load_lds_dwordx4 v[244:245], off
	v_lshl_add_u64 v[244:245], s[8:9], 0, v[160:161]
	s_mov_b32 m0, s77
	s_nop 0
	global_load_lds_dwordx4 v[244:245], off
	s_waitcnt vmcnt(8)
	s_waitcnt lgkmcnt(0)
	s_barrier
	s_setprio 1
	s_waitcnt lgkmcnt(0)
	v_mfma_f32_16x16x32_bf16 v[124:127], v[128:131], v[202:205], v[124:127]
	v_mfma_f32_16x16x32_bf16 v[120:123], v[136:139], v[202:205], v[120:123]
	v_mfma_f32_16x16x32_bf16 v[108:111], v[128:131], v[210:213], v[108:111]
	v_mfma_f32_16x16x32_bf16 v[104:107], v[136:139], v[210:213], v[104:107]
	v_mfma_f32_16x16x32_bf16 v[92:95], v[128:131], v[218:221], v[92:95]
	v_mfma_f32_16x16x32_bf16 v[88:91], v[136:139], v[218:221], v[88:91]
	v_mfma_f32_16x16x32_bf16 v[76:79], v[128:131], v[230:233], v[76:79]
	v_mfma_f32_16x16x32_bf16 v[72:75], v[136:139], v[230:233], v[72:75]
	v_mfma_f32_16x16x32_bf16 v[124:127], v[132:135], v[206:209], v[124:127]
	v_mfma_f32_16x16x32_bf16 v[120:123], v[140:143], v[206:209], v[120:123]
	v_mfma_f32_16x16x32_bf16 v[108:111], v[132:135], v[214:217], v[108:111]
	v_mfma_f32_16x16x32_bf16 v[104:107], v[140:143], v[214:217], v[104:107]
	v_mfma_f32_16x16x32_bf16 v[92:95], v[132:135], v[222:225], v[92:95]
	v_mfma_f32_16x16x32_bf16 v[88:91], v[140:143], v[222:225], v[88:91]
	v_mfma_f32_16x16x32_bf16 v[76:79], v[132:135], v[234:237], v[76:79]
	v_mfma_f32_16x16x32_bf16 v[72:75], v[140:143], v[234:237], v[72:75]
	v_mfma_f32_16x16x32_bf16 v[116:119], v[144:147], v[202:205], v[116:119]
	v_mfma_f32_16x16x32_bf16 v[112:115], v[184:187], v[202:205], v[112:115]
	v_mfma_f32_16x16x32_bf16 v[100:103], v[144:147], v[210:213], v[100:103]
	v_mfma_f32_16x16x32_bf16 v[96:99], v[184:187], v[210:213], v[96:99]
	v_mfma_f32_16x16x32_bf16 v[84:87], v[144:147], v[218:221], v[84:87]
	v_mfma_f32_16x16x32_bf16 v[80:83], v[184:187], v[218:221], v[80:83]
	v_mfma_f32_16x16x32_bf16 v[68:71], v[144:147], v[230:233], v[68:71]
	v_mfma_f32_16x16x32_bf16 v[64:67], v[184:187], v[230:233], v[64:67]
	v_mfma_f32_16x16x32_bf16 v[116:119], v[148:151], v[206:209], v[116:119]
	v_mfma_f32_16x16x32_bf16 v[112:115], v[188:191], v[206:209], v[112:115]
	v_mfma_f32_16x16x32_bf16 v[100:103], v[148:151], v[214:217], v[100:103]
	v_mfma_f32_16x16x32_bf16 v[96:99], v[188:191], v[214:217], v[96:99]
	v_mfma_f32_16x16x32_bf16 v[84:87], v[148:151], v[222:225], v[84:87]
	v_mfma_f32_16x16x32_bf16 v[80:83], v[188:191], v[222:225], v[80:83]
	v_mfma_f32_16x16x32_bf16 v[68:71], v[148:151], v[234:237], v[68:71]
	v_mfma_f32_16x16x32_bf16 v[64:67], v[188:191], v[234:237], v[64:67]
	s_setprio 0
	s_barrier
; #define PG8_STAGE(bufoff, gbase, voff) do { _Pragma("unroll") for (int _i = 0; _i < 2; ++_i) \
;         __builtin_amdgcn_global_load_lds((const unsigned*)((const char*)(gbase) + (voff)[_i]), (PG8_LAS unsigned*)(lds + (bufoff) + ldsw + _i * 8192), 16, 0, 0); } while (0)
; #define PG8_LDA(dst, b, h) do { _Pragma("unroll") for (int m = 0; m < 4; ++m) _Pragma("unroll") for (int k = 0; k < 2; ++k) dst[m][k] = *(const PG8_LAS bf16x8*)(lds + PG8_SA(b, h) + aoff + m * 2048 + k * 1024); } while (0)
; #define PG8_MMA(ai, bj, At, Bt) do { __builtin_amdgcn_s_setprio(1); _Pragma("unroll") for (int m = 0; m < 4; ++m) _Pragma("unroll") for (int n = 0; n < 2; ++n) _Pragma("unroll") for (int k = 0; k < 2; ++k) \
;         acc[ai][bj][m][n] = __builtin_amdgcn_mfma_f32_16x16x32_bf16(Bt[n][k], At[m][k], acc[ai][bj][m][n], 0, 0, 0); __builtin_amdgcn_s_setprio(0); } while (0)
; #define PG8_WAIT_V(n) asm volatile("s_waitcnt vmcnt(" #n ")" ::: "memory")
; #define PG8_WAIT_L(n) asm volatile("s_waitcnt lgkmcnt(" #n ")" ::: "memory")
; #define PG8_BAR __builtin_amdgcn_s_barrier()
; #define PG8_SCHED __builtin_amdgcn_sched_barrier(0)
; template <class Epi, class Sched, bool ALIGN_EPI = false, bool SP2 = false>
; __device__ __forceinline__ void gemm_phase(PG8_LAS unsigned char* lds, const Gemm g, const Sched& S, const Epi& E) {
;     ...
;         for (int t = 0; t < nt; t += 2) {
;     ...
;             PG8_LDA(At, 1, 1); PG8_STAGE(PG8_SB(1, 0), b3, voffB); PG8_STAGE(PG8_SB(1, 1), b3 + hstep, voffB); PG8_STAGE(PG8_SA(1, 0), a3, voffA);
;             PG8_WAIT_V(8); PG8_WAIT_L(0); PG8_BAR; PG8_MMA(1, 0, At, B0); PG8_MMA(1, 1, At, B1); PG8_BAR; PG8_SCHED;
	s_add_i32 s8, s29, s74
	v_lshl_add_u64 v[192:193], v[192:193], 0, s[22:23]
	s_mov_b32 m0, s8
	ds_read_b128 v[202:205], v194 offset:49152
	ds_read_b128 v[206:209], v194 offset:50176
	ds_read_b128 v[210:213], v194 offset:51200
	ds_read_b128 v[214:217], v194 offset:52224
	ds_read_b128 v[218:221], v194 offset:53248
	ds_read_b128 v[222:225], v194 offset:54272
	ds_read_b128 v[230:233], v194 offset:55296
	ds_read_b128 v[234:237], v194 offset:56320
	global_load_lds_dwordx4 v[192:193], off
	s_add_i32 m0, s8, 0x2000
	s_add_u32 s6, s6, 0x40080
	v_lshl_add_u64 v[192:193], v[238:239], 0, s[22:23]
	s_addc_u32 s7, s7, 0
	s_add_i32 s8, s38, s74
	global_load_lds_dwordx4 v[192:193], off
	v_lshl_add_u64 v[192:193], s[6:7], 0, v[158:159]
	s_mov_b32 m0, s8
	s_nop 0
	global_load_lds_dwordx4 v[192:193], off
	v_lshl_add_u64 v[192:193], s[6:7], 0, v[162:163]
	s_add_i32 m0, s8, 0x2000
	s_nop 0
	global_load_lds_dwordx4 v[192:193], off
	v_lshl_add_u64 v[192:193], v[240:241], 0, s[22:23]
	s_mov_b32 m0, s95
	s_nop 0
	global_load_lds_dwordx4 v[192:193], off
	v_lshl_add_u64 v[192:193], v[242:243], 0, s[22:23]
	s_mov_b32 m0, s96
	s_nop 0
	global_load_lds_dwordx4 v[192:193], off
	s_waitcnt vmcnt(8)
	s_waitcnt lgkmcnt(0)
	s_barrier
	s_setprio 1
	s_waitcnt lgkmcnt(0)
	v_mfma_f32_16x16x32_bf16 v[60:63], v[128:131], v[202:205], v[60:63]
	v_mfma_f32_16x16x32_bf16 v[56:59], v[136:139], v[202:205], v[56:59]
	v_mfma_f32_16x16x32_bf16 v[44:47], v[128:131], v[210:213], v[44:47]
	v_mfma_f32_16x16x32_bf16 v[40:43], v[136:139], v[210:213], v[40:43]
	v_mfma_f32_16x16x32_bf16 v[28:31], v[128:131], v[218:221], v[28:31]
	v_mfma_f32_16x16x32_bf16 v[24:27], v[136:139], v[218:221], v[24:27]
	v_mfma_f32_16x16x32_bf16 v[12:15], v[128:131], v[230:233], v[12:15]
	v_mfma_f32_16x16x32_bf16 v[8:11], v[136:139], v[230:233], v[8:11]
	v_mfma_f32_16x16x32_bf16 v[60:63], v[132:135], v[206:209], v[60:63]
	v_mfma_f32_16x16x32_bf16 v[56:59], v[140:143], v[206:209], v[56:59]
	v_mfma_f32_16x16x32_bf16 v[44:47], v[132:135], v[214:217], v[44:47]
	v_mfma_f32_16x16x32_bf16 v[40:43], v[140:143], v[214:217], v[40:43]
	v_mfma_f32_16x16x32_bf16 v[28:31], v[132:135], v[222:225], v[28:31]
	v_mfma_f32_16x16x32_bf16 v[24:27], v[140:143], v[222:225], v[24:27]
	v_mfma_f32_16x16x32_bf16 v[12:15], v[132:135], v[234:237], v[12:15]
	v_mfma_f32_16x16x32_bf16 v[8:11], v[140:143], v[234:237], v[8:11]
	v_mfma_f32_16x16x32_bf16 v[52:55], v[144:147], v[202:205], v[52:55]
	v_mfma_f32_16x16x32_bf16 v[48:51], v[184:187], v[202:205], v[48:51]
	v_mfma_f32_16x16x32_bf16 v[36:39], v[144:147], v[210:213], v[36:39]
	v_mfma_f32_16x16x32_bf16 v[32:35], v[184:187], v[210:213], v[32:35]
	v_mfma_f32_16x16x32_bf16 v[20:23], v[144:147], v[218:221], v[20:23]
	v_mfma_f32_16x16x32_bf16 v[16:19], v[184:187], v[218:221], v[16:19]
	v_mfma_f32_16x16x32_bf16 v[4:7], v[144:147], v[230:233], v[4:7]
	v_mfma_f32_16x16x32_bf16 v[0:3], v[184:187], v[230:233], v[0:3]
	v_mfma_f32_16x16x32_bf16 v[52:55], v[148:151], v[206:209], v[52:55]
	v_mfma_f32_16x16x32_bf16 v[48:51], v[188:191], v[206:209], v[48:51]
	v_mfma_f32_16x16x32_bf16 v[36:39], v[148:151], v[214:217], v[36:39]
	v_mfma_f32_16x16x32_bf16 v[32:35], v[188:191], v[214:217], v[32:35]
	v_mfma_f32_16x16x32_bf16 v[20:23], v[148:151], v[222:225], v[20:23]
	v_mfma_f32_16x16x32_bf16 v[16:19], v[188:191], v[222:225], v[16:19]
	v_mfma_f32_16x16x32_bf16 v[4:7], v[148:151], v[234:237], v[4:7]
	v_mfma_f32_16x16x32_bf16 v[0:3], v[188:191], v[234:237], v[0:3]
	s_setprio 0
	s_barrier
	s_mov_b32 s99, 0
	s_add_i32 s27, s27, 2
	s_add_u32 s4, s4, 0x100
	s_addc_u32 s5, s5, 0
	s_add_u32 s24, s24, 0x100
	s_addc_u32 s25, s25, 0
	s_cmp_gt_u32 s27, 13
	s_cbranch_scc0 .LBB0_121
	s_and_b64 vcc, exec, s[70:71]
	s_cbranch_vccz .LBB0_124
	s_barrier

; #define PG8_STAGE(bufoff, gbase, voff) do { _Pragma("unroll") for (int _i = 0; _i < 2; ++_i) \
;         __builtin_amdgcn_global_load_lds((const unsigned*)((const char*)(gbase) + (voff)[_i]), (PG8_LAS unsigned*)(lds + (bufoff) + ldsw + _i * 8192), 16, 0, 0); } while (0)
; #define PG8_LDA(dst, b, h) do { _Pragma("unroll") for (int m = 0; m < 4; ++m) _Pragma("unroll") for (int k = 0; k < 2; ++k) dst[m][k] = *(const PG8_LAS bf16x8*)(lds + PG8_SA(b, h) + aoff + m * 2048 + k * 1024); } while (0)
; #define PG8_LDB(dst, b, h) do { _Pragma("unroll") for (int n = 0; n < 2; ++n) _Pragma("unroll") for (int k = 0; k < 2; ++k) dst[n][k] = *(const PG8_LAS bf16x8*)(lds + PG8_SB(b, h) + boff + n * 2048 + k * 1024); } while (0)
; #define PG8_MMA(ai, bj, At, Bt) do { __builtin_amdgcn_s_setprio(1); _Pragma("unroll") for (int m = 0; m < 4; ++m) _Pragma("unroll") for (int n = 0; n < 2; ++n) _Pragma("unroll") for (int k = 0; k < 2; ++k) \
;         acc[ai][bj][m][n] = __builtin_amdgcn_mfma_f32_16x16x32_bf16(Bt[n][k], At[m][k], acc[ai][bj][m][n], 0, 0, 0); __builtin_amdgcn_s_setprio(0); } while (0)
; #define PG8_WAIT_V(n) asm volatile("s_waitcnt vmcnt(" #n ")" ::: "memory")
; #define PG8_WAIT_L(n) asm volatile("s_waitcnt lgkmcnt(" #n ")" ::: "memory")
; #define PG8_BAR __builtin_amdgcn_s_barrier()
; #define PG8_SCHED __builtin_amdgcn_sched_barrier(0)
; template <class Epi, class Sched, bool ALIGN_EPI = false, bool SP2 = false>
; __device__ __forceinline__ void gemm_phase(PG8_LAS unsigned char* lds, const Gemm g, const Sched& S, const Epi& E) {
;     ...
;             PG8_LDB(B0, 0, 0); PG8_LDB(B1, 0, 1); PG8_SCHED; PG8_LDA(At, 0, 0); PG8_STAGE(PG8_SA(1, 1), a1 + hstep, voffA);
;             PG8_WAIT_V(8); PG8_WAIT_L(0); PG8_BAR; PG8_MMA(0, 0, At, B0); PG8_MMA(0, 1, At, B1); PG8_BAR; PG8_SCHED;
;             PG8_LDA(At, 0, 1); PG8_STAGE(PG8_SB(0, 0), b2, voffB); PG8_STAGE(PG8_SB(0, 1), b2 + hstep, voffB); PG8_STAGE(PG8_SA(0, 0), a2, voffA);
;             PG8_WAIT_V(8); PG8_WAIT_L(0); PG8_BAR; PG8_MMA(1, 0, At, B0); PG8_MMA(1, 1, At, B1); PG8_BAR; PG8_SCHED;
.Lrj_P3a_0:
	s_waitcnt lgkmcnt(0)
	s_barrier
	s_setprio 1
	s_waitcnt lgkmcnt(0)
	v_mfma_f32_16x16x32_bf16 v[124:127], v[144:147], v[184:187], v[124:127]
	v_mfma_f32_16x16x32_bf16 v[120:123], v[160:163], v[184:187], v[120:123]
	v_mfma_f32_16x16x32_bf16 v[112:115], v[144:147], v[192:195], v[112:115]
	v_mfma_f32_16x16x32_bf16 v[104:107], v[160:163], v[192:195], v[104:107]
	v_mfma_f32_16x16x32_bf16 v[96:99], v[144:147], v[200:203], v[96:99]
	v_mfma_f32_16x16x32_bf16 v[88:91], v[160:163], v[200:203], v[88:91]
	v_mfma_f32_16x16x32_bf16 v[80:83], v[144:147], v[208:211], v[80:83]
	v_mfma_f32_16x16x32_bf16 v[72:75], v[160:163], v[208:211], v[72:75]
	v_mfma_f32_16x16x32_bf16 v[124:127], v[156:159], v[188:191], v[124:127]
	v_mfma_f32_16x16x32_bf16 v[120:123], v[164:167], v[188:191], v[120:123]
	v_mfma_f32_16x16x32_bf16 v[112:115], v[156:159], v[196:199], v[112:115]
	v_mfma_f32_16x16x32_bf16 v[104:107], v[164:167], v[196:199], v[104:107]
	v_mfma_f32_16x16x32_bf16 v[96:99], v[156:159], v[204:207], v[96:99]
	v_mfma_f32_16x16x32_bf16 v[88:91], v[164:167], v[204:207], v[88:91]
	v_mfma_f32_16x16x32_bf16 v[80:83], v[156:159], v[212:215], v[80:83]
	v_mfma_f32_16x16x32_bf16 v[72:75], v[164:167], v[212:215], v[72:75]
	v_mfma_f32_16x16x32_bf16 v[116:119], v[168:171], v[184:187], v[116:119]
	v_mfma_f32_16x16x32_bf16 v[108:111], v[176:179], v[184:187], v[108:111]
	v_mfma_f32_16x16x32_bf16 v[100:103], v[168:171], v[192:195], v[100:103]
	v_mfma_f32_16x16x32_bf16 v[92:95], v[176:179], v[192:195], v[92:95]
	v_mfma_f32_16x16x32_bf16 v[84:87], v[168:171], v[200:203], v[84:87]
	v_mfma_f32_16x16x32_bf16 v[76:79], v[176:179], v[200:203], v[76:79]
	v_mfma_f32_16x16x32_bf16 v[68:71], v[168:171], v[208:211], v[68:71]
	v_mfma_f32_16x16x32_bf16 v[64:67], v[176:179], v[208:211], v[64:67]
	v_mfma_f32_16x16x32_bf16 v[116:119], v[172:175], v[188:191], v[116:119]
	v_mfma_f32_16x16x32_bf16 v[108:111], v[180:183], v[188:191], v[108:111]
	v_mfma_f32_16x16x32_bf16 v[100:103], v[172:175], v[196:199], v[100:103]
	v_mfma_f32_16x16x32_bf16 v[92:95], v[180:183], v[196:199], v[92:95]
	v_mfma_f32_16x16x32_bf16 v[84:87], v[172:175], v[204:207], v[84:87]
	v_mfma_f32_16x16x32_bf16 v[76:79], v[180:183], v[204:207], v[76:79]
	v_mfma_f32_16x16x32_bf16 v[68:71], v[172:175], v[212:215], v[68:71]
	v_mfma_f32_16x16x32_bf16 v[64:67], v[180:183], v[212:215], v[64:67]
	s_setprio 0
	s_barrier
	s_add_i32 s75, s67, s43
	v_lshl_add_u64 v[148:149], s[38:39], 0, v[132:133]
	s_mov_b32 m0, s75
	ds_read_b128 v[184:187], v155 offset:16384
	ds_read_b128 v[188:191], v155 offset:17408
	ds_read_b128 v[192:195], v155 offset:18432
	ds_read_b128 v[196:199], v155 offset:19456
	ds_read_b128 v[200:203], v155 offset:20480
	ds_read_b128 v[204:207], v155 offset:21504
	ds_read_b128 v[208:211], v155 offset:22528
	ds_read_b128 v[212:215], v155 offset:23552
	global_load_lds_dwordx4 v[148:149], off
	s_add_i32 m0, s75, 0x2000
	s_add_u32 s76, s38, 0x20000
	v_lshl_add_u64 v[216:217], s[38:39], 0, v[128:129]
	s_addc_u32 s77, s39, 0
	s_add_i32 s75, s68, s43
	global_load_lds_dwordx4 v[216:217], off
	v_lshl_add_u64 v[218:219], s[76:77], 0, v[132:133]
	s_mov_b32 m0, s75
	v_lshl_add_u64 v[220:221], s[40:41], 0, v[130:131]
	global_load_lds_dwordx4 v[218:219], off
	v_lshl_add_u64 v[218:219], s[76:77], 0, v[128:129]
	s_add_i32 m0, s75, 0x2000
	s_nop 0
	global_load_lds_dwordx4 v[218:219], off
	v_lshl_add_u64 v[218:219], s[40:41], 0, v[134:135]
	s_mov_b32 m0, s35
	s_nop 0
	global_load_lds_dwordx4 v[218:219], off
	s_mov_b32 m0, s52
	s_nop 0
	global_load_lds_dwordx4 v[220:221], off
	s_cmp_eq_u32 s99, 1
	s_cbranch_scc1 .Lrw_P3a_1
	s_waitcnt vmcnt(8)
	s_branch .Lrj_P3a_1

; #define PG8_STAGE(bufoff, gbase, voff) do { _Pragma("unroll") for (int _i = 0; _i < 2; ++_i) \
;         __builtin_amdgcn_global_load_lds((const unsigned*)((const char*)(gbase) + (voff)[_i]), (PG8_LAS unsigned*)(lds + (bufoff) + ldsw + _i * 8192), 16, 0, 0); } while (0)
; #define PG8_LDA(dst, b, h) do { _Pragma("unroll") for (int m = 0; m < 4; ++m) _Pragma("unroll") for (int k = 0; k < 2; ++k) dst[m][k] = *(const PG8_LAS bf16x8*)(lds + PG8_SA(b, h) + aoff + m * 2048 + k * 1024); } while (0)
; #define PG8_LDB(dst, b, h) do { _Pragma("unroll") for (int n = 0; n < 2; ++n) _Pragma("unroll") for (int k = 0; k < 2; ++k) dst[n][k] = *(const PG8_LAS bf16x8*)(lds + PG8_SB(b, h) + boff + n * 2048 + k * 1024); } while (0)
; #define PG8_MMA(ai, bj, At, Bt) do { __builtin_amdgcn_s_setprio(1); _Pragma("unroll") for (int m = 0; m < 4; ++m) _Pragma("unroll") for (int n = 0; n < 2; ++n) _Pragma("unroll") for (int k = 0; k < 2; ++k) \
;         acc[ai][bj][m][n] = __builtin_amdgcn_mfma_f32_16x16x32_bf16(Bt[n][k], At[m][k], acc[ai][bj][m][n], 0, 0, 0); __builtin_amdgcn_s_setprio(0); } while (0)
; #define PG8_WAIT_V(n) asm volatile("s_waitcnt vmcnt(" #n ")" ::: "memory")
; #define PG8_WAIT_L(n) asm volatile("s_waitcnt lgkmcnt(" #n ")" ::: "memory")
; #define PG8_BAR __builtin_amdgcn_s_barrier()
; #define PG8_SCHED __builtin_amdgcn_sched_barrier(0)
; template <class Epi, class Sched, bool ALIGN_EPI = false, bool SP2 = false>
; __device__ __forceinline__ void gemm_phase(PG8_LAS unsigned char* lds, const Gemm g, const Sched& S, const Epi& E) {
;     ...
;             PG8_WAIT_V(8); PG8_WAIT_L(0); PG8_BAR; PG8_MMA(1, 0, At, B0); PG8_MMA(1, 1, At, B1); PG8_BAR; PG8_SCHED;
;             PG8_LDB(B0, 1, 0); PG8_LDB(B1, 1, 1); PG8_SCHED; PG8_LDA(At, 1, 0); PG8_STAGE(PG8_SA(0, 1), a2 + hstep, voffA);
;             PG8_WAIT_V(8); PG8_WAIT_L(0); PG8_BAR; PG8_MMA(0, 0, At, B0); PG8_MMA(0, 1, At, B1); PG8_BAR; PG8_SCHED;
.Lrj_P3a_1:
	s_waitcnt lgkmcnt(0)
	s_barrier
	s_setprio 1
	s_waitcnt lgkmcnt(0)
	v_mfma_f32_16x16x32_bf16 v[60:63], v[144:147], v[184:187], v[60:63]
	v_mfma_f32_16x16x32_bf16 v[56:59], v[160:163], v[184:187], v[56:59]
	v_mfma_f32_16x16x32_bf16 v[48:51], v[144:147], v[192:195], v[48:51]
	v_mfma_f32_16x16x32_bf16 v[40:43], v[160:163], v[192:195], v[40:43]
	v_mfma_f32_16x16x32_bf16 v[32:35], v[144:147], v[200:203], v[32:35]
	v_mfma_f32_16x16x32_bf16 v[24:27], v[160:163], v[200:203], v[24:27]
	v_mfma_f32_16x16x32_bf16 v[16:19], v[144:147], v[208:211], v[16:19]
	v_mfma_f32_16x16x32_bf16 v[8:11], v[160:163], v[208:211], v[8:11]
	v_mfma_f32_16x16x32_bf16 v[60:63], v[156:159], v[188:191], v[60:63]
	v_mfma_f32_16x16x32_bf16 v[56:59], v[164:167], v[188:191], v[56:59]
	v_mfma_f32_16x16x32_bf16 v[48:51], v[156:159], v[196:199], v[48:51]
	v_mfma_f32_16x16x32_bf16 v[40:43], v[164:167], v[196:199], v[40:43]
	v_mfma_f32_16x16x32_bf16 v[32:35], v[156:159], v[204:207], v[32:35]
	v_mfma_f32_16x16x32_bf16 v[24:27], v[164:167], v[204:207], v[24:27]
	v_mfma_f32_16x16x32_bf16 v[16:19], v[156:159], v[212:215], v[16:19]
	v_mfma_f32_16x16x32_bf16 v[8:11], v[164:167], v[212:215], v[8:11]
	v_mfma_f32_16x16x32_bf16 v[52:55], v[168:171], v[184:187], v[52:55]
	v_mfma_f32_16x16x32_bf16 v[44:47], v[176:179], v[184:187], v[44:47]
	v_mfma_f32_16x16x32_bf16 v[36:39], v[168:171], v[192:195], v[36:39]
	v_mfma_f32_16x16x32_bf16 v[28:31], v[176:179], v[192:195], v[28:31]
	v_mfma_f32_16x16x32_bf16 v[20:23], v[168:171], v[200:203], v[20:23]
	v_mfma_f32_16x16x32_bf16 v[12:15], v[176:179], v[200:203], v[12:15]
	v_mfma_f32_16x16x32_bf16 v[4:7], v[168:171], v[208:211], v[4:7]
	v_mfma_f32_16x16x32_bf16 v[0:3], v[176:179], v[208:211], v[0:3]
	v_mfma_f32_16x16x32_bf16 v[52:55], v[172:175], v[188:191], v[52:55]
	v_mfma_f32_16x16x32_bf16 v[44:47], v[180:183], v[188:191], v[44:47]
	v_mfma_f32_16x16x32_bf16 v[36:39], v[172:175], v[196:199], v[36:39]
	v_mfma_f32_16x16x32_bf16 v[28:31], v[180:183], v[196:199], v[28:31]
	v_mfma_f32_16x16x32_bf16 v[20:23], v[172:175], v[204:207], v[20:23]
	v_mfma_f32_16x16x32_bf16 v[12:15], v[180:183], v[204:207], v[12:15]
	v_mfma_f32_16x16x32_bf16 v[4:7], v[172:175], v[212:215], v[4:7]
	v_mfma_f32_16x16x32_bf16 v[0:3], v[180:183], v[212:215], v[0:3]
	s_setprio 0
	s_barrier
	s_add_i32 s75, 0, 0x18000
	s_add_i32 s76, 0, 0x1c000
	v_add_u32_e32 v164, s75, v151
	v_add_u32_e32 v180, s76, v151
	ds_read_b128 v[144:147], v164
	ds_read_b128 v[156:159], v164 offset:1024
	ds_read_b128 v[160:163], v164 offset:2048
	ds_read_b128 v[164:167], v164 offset:3072
	ds_read_b128 v[168:171], v180
	ds_read_b128 v[172:175], v180 offset:1024
	ds_read_b128 v[176:179], v180 offset:2048
	ds_read_b128 v[180:183], v180 offset:3072
	s_add_u32 s40, s40, 0x20000
	s_addc_u32 s41, s41, 0
	s_mov_b32 m0, s53
	v_lshl_add_u64 v[222:223], s[40:41], 0, v[134:135]
	ds_read_b128 v[184:187], v155 offset:32768
	ds_read_b128 v[188:191], v155 offset:33792
	ds_read_b128 v[192:195], v155 offset:34816
	ds_read_b128 v[196:199], v155 offset:35840
	ds_read_b128 v[200:203], v155 offset:36864
	ds_read_b128 v[204:207], v155 offset:37888
	ds_read_b128 v[208:211], v155 offset:38912
	ds_read_b128 v[212:215], v155 offset:39936
	global_load_lds_dwordx4 v[222:223], off
	v_lshl_add_u64 v[222:223], s[40:41], 0, v[130:131]
	s_mov_b32 m0, s60
	s_nop 0
	global_load_lds_dwordx4 v[222:223], off
	s_waitcnt vmcnt(8)
	s_waitcnt lgkmcnt(0)
	s_barrier
	s_setprio 1
	s_waitcnt lgkmcnt(0)
	v_mfma_f32_16x16x32_bf16 v[124:127], v[144:147], v[184:187], v[124:127]
	v_mfma_f32_16x16x32_bf16 v[120:123], v[160:163], v[184:187], v[120:123]
	v_mfma_f32_16x16x32_bf16 v[112:115], v[144:147], v[192:195], v[112:115]
	v_mfma_f32_16x16x32_bf16 v[104:107], v[160:163], v[192:195], v[104:107]
	v_mfma_f32_16x16x32_bf16 v[96:99], v[144:147], v[200:203], v[96:99]
	v_mfma_f32_16x16x32_bf16 v[88:91], v[160:163], v[200:203], v[88:91]
	v_mfma_f32_16x16x32_bf16 v[80:83], v[144:147], v[208:211], v[80:83]
	v_mfma_f32_16x16x32_bf16 v[72:75], v[160:163], v[208:211], v[72:75]
	v_mfma_f32_16x16x32_bf16 v[124:127], v[156:159], v[188:191], v[124:127]
	v_mfma_f32_16x16x32_bf16 v[120:123], v[164:167], v[188:191], v[120:123]
	v_mfma_f32_16x16x32_bf16 v[112:115], v[156:159], v[196:199], v[112:115]
	v_mfma_f32_16x16x32_bf16 v[104:107], v[164:167], v[196:199], v[104:107]
	v_mfma_f32_16x16x32_bf16 v[96:99], v[156:159], v[204:207], v[96:99]
	v_mfma_f32_16x16x32_bf16 v[88:91], v[164:167], v[204:207], v[88:91]
	v_mfma_f32_16x16x32_bf16 v[80:83], v[156:159], v[212:215], v[80:83]
	v_mfma_f32_16x16x32_bf16 v[72:75], v[164:167], v[212:215], v[72:75]
	v_mfma_f32_16x16x32_bf16 v[116:119], v[168:171], v[184:187], v[116:119]
	v_mfma_f32_16x16x32_bf16 v[108:111], v[176:179], v[184:187], v[108:111]
	v_mfma_f32_16x16x32_bf16 v[100:103], v[168:171], v[192:195], v[100:103]
	v_mfma_f32_16x16x32_bf16 v[92:95], v[176:179], v[192:195], v[92:95]
	v_mfma_f32_16x16x32_bf16 v[84:87], v[168:171], v[200:203], v[84:87]
	v_mfma_f32_16x16x32_bf16 v[76:79], v[176:179], v[200:203], v[76:79]
	v_mfma_f32_16x16x32_bf16 v[68:71], v[168:171], v[208:211], v[68:71]
	v_mfma_f32_16x16x32_bf16 v[64:67], v[176:179], v[208:211], v[64:67]
	v_mfma_f32_16x16x32_bf16 v[116:119], v[172:175], v[188:191], v[116:119]
	v_mfma_f32_16x16x32_bf16 v[108:111], v[180:183], v[188:191], v[108:111]
	v_mfma_f32_16x16x32_bf16 v[100:103], v[172:175], v[196:199], v[100:103]
	v_mfma_f32_16x16x32_bf16 v[92:95], v[180:183], v[196:199], v[92:95]
	v_mfma_f32_16x16x32_bf16 v[84:87], v[172:175], v[204:207], v[84:87]
	v_mfma_f32_16x16x32_bf16 v[76:79], v[180:183], v[204:207], v[76:79]
	v_mfma_f32_16x16x32_bf16 v[68:71], v[172:175], v[212:215], v[68:71]
	v_mfma_f32_16x16x32_bf16 v[64:67], v[180:183], v[212:215], v[64:67]
	s_setprio 0
	s_barrier
; #define PG8_STAGE(bufoff, gbase, voff) do { _Pragma("unroll") for (int _i = 0; _i < 2; ++_i) \
;         __builtin_amdgcn_global_load_lds((const unsigned*)((const char*)(gbase) + (voff)[_i]), (PG8_LAS unsigned*)(lds + (bufoff) + ldsw + _i * 8192), 16, 0, 0); } while (0)
; #define PG8_LDA(dst, b, h) do { _Pragma("unroll") for (int m = 0; m < 4; ++m) _Pragma("unroll") for (int k = 0; k < 2; ++k) dst[m][k] = *(const PG8_LAS bf16x8*)(lds + PG8_SA(b, h) + aoff + m * 2048 + k * 1024); } while (0)
; #define PG8_MMA(ai, bj, At, Bt) do { __builtin_amdgcn_s_setprio(1); _Pragma("unroll") for (int m = 0; m < 4; ++m) _Pragma("unroll") for (int n = 0; n < 2; ++n) _Pragma("unroll") for (int k = 0; k < 2; ++k) \
;         acc[ai][bj][m][n] = __builtin_amdgcn_mfma_f32_16x16x32_bf16(Bt[n][k], At[m][k], acc[ai][bj][m][n], 0, 0, 0); __builtin_amdgcn_s_setprio(0); } while (0)
; #define PG8_WAIT_V(n) asm volatile("s_waitcnt vmcnt(" #n ")" ::: "memory")
; #define PG8_WAIT_L(n) asm volatile("s_waitcnt lgkmcnt(" #n ")" ::: "memory")
; #define PG8_BAR __builtin_amdgcn_s_barrier()
; #define PG8_SCHED __builtin_amdgcn_sched_barrier(0)
; template <class Epi, class Sched, bool ALIGN_EPI = false, bool SP2 = false>
; __device__ __forceinline__ void gemm_phase(PG8_LAS unsigned char* lds, const Gemm g, const Sched& S, const Epi& E) {
;     ...
;             PG8_LDA(At, 1, 1); PG8_STAGE(PG8_SB(1, 0), b3, voffB); PG8_STAGE(PG8_SB(1, 1), b3 + hstep, voffB); PG8_STAGE(PG8_SA(1, 0), a3, voffA);
;             PG8_WAIT_V(8); PG8_WAIT_L(0); PG8_BAR; PG8_MMA(1, 0, At, B0); PG8_MMA(1, 1, At, B1); PG8_BAR; PG8_SCHED;
;     ...
;         if constexpr (ALIGN_EPI) { if (wr == 0) PG8_BAR; }
	s_add_i32 s40, s75, s43
	v_lshl_add_u64 v[148:149], v[148:149], 0, s[12:13]
	s_mov_b32 m0, s40
	ds_read_b128 v[184:187], v155 offset:49152
	ds_read_b128 v[188:191], v155 offset:50176
	ds_read_b128 v[192:195], v155 offset:51200
	ds_read_b128 v[196:199], v155 offset:52224
	ds_read_b128 v[200:203], v155 offset:53248
	ds_read_b128 v[204:207], v155 offset:54272
	ds_read_b128 v[208:211], v155 offset:55296
	ds_read_b128 v[212:215], v155 offset:56320
	global_load_lds_dwordx4 v[148:149], off
	s_add_i32 m0, s40, 0x2000
	s_add_u32 s38, s38, 0x20080
	v_lshl_add_u64 v[148:149], v[216:217], 0, s[12:13]
	s_addc_u32 s39, s39, 0
	s_add_i32 s40, s76, s43
	global_load_lds_dwordx4 v[148:149], off
	v_lshl_add_u64 v[148:149], s[38:39], 0, v[132:133]
	s_mov_b32 m0, s40
	s_nop 0
	global_load_lds_dwordx4 v[148:149], off
	v_lshl_add_u64 v[148:149], s[38:39], 0, v[128:129]
	s_add_i32 m0, s40, 0x2000
	s_nop 0
	global_load_lds_dwordx4 v[148:149], off
	v_lshl_add_u64 v[148:149], v[218:219], 0, s[12:13]
	s_mov_b32 m0, s64
	s_nop 0
	global_load_lds_dwordx4 v[148:149], off
	v_lshl_add_u64 v[148:149], v[220:221], 0, s[12:13]
	s_mov_b32 m0, s65
	s_nop 0
	global_load_lds_dwordx4 v[148:149], off
	s_waitcnt vmcnt(8)
	s_waitcnt lgkmcnt(0)
	s_barrier
	s_setprio 1
	s_waitcnt lgkmcnt(0)
	v_mfma_f32_16x16x32_bf16 v[60:63], v[144:147], v[184:187], v[60:63]
	v_mfma_f32_16x16x32_bf16 v[56:59], v[160:163], v[184:187], v[56:59]
	v_mfma_f32_16x16x32_bf16 v[48:51], v[144:147], v[192:195], v[48:51]
	v_mfma_f32_16x16x32_bf16 v[40:43], v[160:163], v[192:195], v[40:43]
	v_mfma_f32_16x16x32_bf16 v[32:35], v[144:147], v[200:203], v[32:35]
	v_mfma_f32_16x16x32_bf16 v[24:27], v[160:163], v[200:203], v[24:27]
	v_mfma_f32_16x16x32_bf16 v[16:19], v[144:147], v[208:211], v[16:19]
	v_mfma_f32_16x16x32_bf16 v[8:11], v[160:163], v[208:211], v[8:11]
	v_mfma_f32_16x16x32_bf16 v[60:63], v[156:159], v[188:191], v[60:63]
	v_mfma_f32_16x16x32_bf16 v[56:59], v[164:167], v[188:191], v[56:59]
	v_mfma_f32_16x16x32_bf16 v[48:51], v[156:159], v[196:199], v[48:51]
	v_mfma_f32_16x16x32_bf16 v[40:43], v[164:167], v[196:199], v[40:43]
	v_mfma_f32_16x16x32_bf16 v[32:35], v[156:159], v[204:207], v[32:35]
	v_mfma_f32_16x16x32_bf16 v[24:27], v[164:167], v[204:207], v[24:27]
	v_mfma_f32_16x16x32_bf16 v[16:19], v[156:159], v[212:215], v[16:19]
	v_mfma_f32_16x16x32_bf16 v[8:11], v[164:167], v[212:215], v[8:11]
	v_mfma_f32_16x16x32_bf16 v[52:55], v[168:171], v[184:187], v[52:55]
	v_mfma_f32_16x16x32_bf16 v[44:47], v[176:179], v[184:187], v[44:47]
	v_mfma_f32_16x16x32_bf16 v[36:39], v[168:171], v[192:195], v[36:39]
	v_mfma_f32_16x16x32_bf16 v[28:31], v[176:179], v[192:195], v[28:31]
	v_mfma_f32_16x16x32_bf16 v[20:23], v[168:171], v[200:203], v[20:23]
	v_mfma_f32_16x16x32_bf16 v[12:15], v[176:179], v[200:203], v[12:15]
	v_mfma_f32_16x16x32_bf16 v[4:7], v[168:171], v[208:211], v[4:7]
	v_mfma_f32_16x16x32_bf16 v[0:3], v[176:179], v[208:211], v[0:3]
	v_mfma_f32_16x16x32_bf16 v[52:55], v[172:175], v[188:191], v[52:55]
	v_mfma_f32_16x16x32_bf16 v[44:47], v[180:183], v[188:191], v[44:47]
	v_mfma_f32_16x16x32_bf16 v[36:39], v[172:175], v[196:199], v[36:39]
	v_mfma_f32_16x16x32_bf16 v[28:31], v[180:183], v[196:199], v[28:31]
	v_mfma_f32_16x16x32_bf16 v[20:23], v[172:175], v[204:207], v[20:23]
	v_mfma_f32_16x16x32_bf16 v[12:15], v[180:183], v[204:207], v[12:15]
	v_mfma_f32_16x16x32_bf16 v[4:7], v[172:175], v[212:215], v[4:7]
	v_mfma_f32_16x16x32_bf16 v[0:3], v[180:183], v[212:215], v[0:3]
	s_setprio 0
	s_barrier
	s_mov_b32 s99, 0
	s_add_i32 s74, s74, 2
	s_add_u32 s36, s36, 0x100
	s_addc_u32 s37, s37, 0
	s_add_u32 s72, s72, 0x100
	s_addc_u32 s73, s73, 0
	s_cmp_gt_u32 s74, 5
	s_cbranch_scc0 .LBB0_1284
	s_and_b64 vcc, exec, s[14:15]
	s_cbranch_vccz .LBB0_1287
	s_barrier

; #define PG8_STAGE(bufoff, gbase, voff) do { _Pragma("unroll") for (int _i = 0; _i < 2; ++_i) \
;         __builtin_amdgcn_global_load_lds((const unsigned*)((const char*)(gbase) + (voff)[_i]), (PG8_LAS unsigned*)(lds + (bufoff) + ldsw + _i * 8192), 16, 0, 0); } while (0)
; #define PG8_LDA(dst, b, h) do { _Pragma("unroll") for (int m = 0; m < 4; ++m) _Pragma("unroll") for (int k = 0; k < 2; ++k) dst[m][k] = *(const PG8_LAS bf16x8*)(lds + PG8_SA(b, h) + aoff + m * 2048 + k * 1024); } while (0)
; #define PG8_LDB(dst, b, h) do { _Pragma("unroll") for (int n = 0; n < 2; ++n) _Pragma("unroll") for (int k = 0; k < 2; ++k) dst[n][k] = *(const PG8_LAS bf16x8*)(lds + PG8_SB(b, h) + boff + n * 2048 + k * 1024); } while (0)
; #define PG8_MMA(ai, bj, At, Bt) do { __builtin_amdgcn_s_setprio(1); _Pragma("unroll") for (int m = 0; m < 4; ++m) _Pragma("unroll") for (int n = 0; n < 2; ++n) _Pragma("unroll") for (int k = 0; k < 2; ++k) \
;         acc[ai][bj][m][n] = __builtin_amdgcn_mfma_f32_16x16x32_bf16(Bt[n][k], At[m][k], acc[ai][bj][m][n], 0, 0, 0); __builtin_amdgcn_s_setprio(0); } while (0)
; #define PG8_WAIT_V(n) asm volatile("s_waitcnt vmcnt(" #n ")" ::: "memory")
; #define PG8_WAIT_L(n) asm volatile("s_waitcnt lgkmcnt(" #n ")" ::: "memory")
; #define PG8_BAR __builtin_amdgcn_s_barrier()
; #define PG8_SCHED __builtin_amdgcn_sched_barrier(0)
; template <class Epi, class Sched, bool ALIGN_EPI = false, bool SP2 = false>
; __device__ __forceinline__ void gemm_phase(PG8_LAS unsigned char* lds, const Gemm g, const Sched& S, const Epi& E) {
;     ...
;             PG8_LDB(B0, 0, 0); PG8_LDB(B1, 0, 1); PG8_SCHED; PG8_LDA(At, 0, 0); PG8_STAGE(PG8_SA(1, 1), a1 + hstep, voffA);
;             PG8_WAIT_V(8); PG8_WAIT_L(0); PG8_BAR; PG8_MMA(0, 0, At, B0); PG8_MMA(0, 1, At, B1); PG8_BAR; PG8_SCHED;
;             PG8_LDA(At, 0, 1); PG8_STAGE(PG8_SB(0, 0), b2, voffB); PG8_STAGE(PG8_SB(0, 1), b2 + hstep, voffB); PG8_STAGE(PG8_SA(0, 0), a2, voffA);
.Lrj_P3b_0:
	s_waitcnt lgkmcnt(0)
	s_barrier
	s_setprio 1
	s_waitcnt lgkmcnt(0)
	v_mfma_f32_16x16x32_bf16 v[64:67], v[0:3], v[32:35], 0
	v_mfma_f32_16x16x32_bf16 v[68:71], v[8:11], v[32:35], 0
	v_mfma_f32_16x16x32_bf16 v[72:75], v[0:3], v[40:43], 0
	v_mfma_f32_16x16x32_bf16 v[76:79], v[8:11], v[40:43], 0
	v_mfma_f32_16x16x32_bf16 v[80:83], v[0:3], v[48:51], 0
	v_mfma_f32_16x16x32_bf16 v[84:87], v[8:11], v[48:51], 0
	v_mfma_f32_16x16x32_bf16 v[88:91], v[0:3], v[56:59], 0
	v_mfma_f32_16x16x32_bf16 v[92:95], v[8:11], v[56:59], 0
	v_mfma_f32_16x16x32_bf16 v[64:67], v[4:7], v[36:39], v[64:67]
	v_mfma_f32_16x16x32_bf16 v[68:71], v[12:15], v[36:39], v[68:71]
	v_mfma_f32_16x16x32_bf16 v[72:75], v[4:7], v[44:47], v[72:75]
	v_mfma_f32_16x16x32_bf16 v[76:79], v[12:15], v[44:47], v[76:79]
	v_mfma_f32_16x16x32_bf16 v[80:83], v[4:7], v[52:55], v[80:83]
	v_mfma_f32_16x16x32_bf16 v[84:87], v[12:15], v[52:55], v[84:87]
	v_mfma_f32_16x16x32_bf16 v[88:91], v[4:7], v[60:63], v[88:91]
	v_mfma_f32_16x16x32_bf16 v[92:95], v[12:15], v[60:63], v[92:95]
	v_mfma_f32_16x16x32_bf16 v[96:99], v[16:19], v[32:35], 0
	v_mfma_f32_16x16x32_bf16 v[32:35], v[24:27], v[32:35], 0
	v_mfma_f32_16x16x32_bf16 v[96:99], v[20:23], v[36:39], v[96:99]
	v_mfma_f32_16x16x32_bf16 v[32:35], v[28:31], v[36:39], v[32:35]
	v_mfma_f32_16x16x32_bf16 v[36:39], v[16:19], v[40:43], 0
	v_mfma_f32_16x16x32_bf16 v[40:43], v[24:27], v[40:43], 0
	v_mfma_f32_16x16x32_bf16 v[36:39], v[20:23], v[44:47], v[36:39]
	v_mfma_f32_16x16x32_bf16 v[40:43], v[28:31], v[44:47], v[40:43]
	v_mfma_f32_16x16x32_bf16 v[44:47], v[16:19], v[48:51], 0
	v_mfma_f32_16x16x32_bf16 v[48:51], v[24:27], v[48:51], 0
	v_mfma_f32_16x16x32_bf16 v[44:47], v[20:23], v[52:55], v[44:47]
	v_mfma_f32_16x16x32_bf16 v[48:51], v[28:31], v[52:55], v[48:51]
	v_mfma_f32_16x16x32_bf16 v[52:55], v[16:19], v[56:59], 0
	v_mfma_f32_16x16x32_bf16 v[56:59], v[24:27], v[56:59], 0
	v_mfma_f32_16x16x32_bf16 v[52:55], v[20:23], v[60:63], v[52:55]
	v_mfma_f32_16x16x32_bf16 v[56:59], v[28:31], v[60:63], v[56:59]
	s_setprio 0
	s_barrier
	v_lshl_add_u64 v[144:145], s[62:63], 0, v[132:133]
	s_mov_b32 m0, s75
	v_lshl_add_u64 v[140:141], v[144:145], 0, s[20:21]
	v_lshl_add_u64 v[214:215], s[62:63], 0, v[128:129]
	s_add_u32 s88, s62, 0x10100
	ds_read_b128 v[60:63], v151 offset:16384
	ds_read_b128 v[100:103], v151 offset:17408
	ds_read_b128 v[104:107], v151 offset:18432
	ds_read_b128 v[108:111], v151 offset:19456
	ds_read_b128 v[112:115], v151 offset:20480
	ds_read_b128 v[116:119], v151 offset:21504
	ds_read_b128 v[120:123], v151 offset:22528
	ds_read_b128 v[124:127], v151 offset:23552
	global_load_lds_dwordx4 v[140:141], off
	v_lshl_add_u64 v[140:141], v[214:215], 0, s[20:21]
	s_mov_b32 m0, s76
	s_addc_u32 s89, s63, 0
	global_load_lds_dwordx4 v[140:141], off
	v_lshl_add_u64 v[140:141], s[88:89], 0, v[132:133]
	s_mov_b32 m0, s77
	v_lshl_add_u64 v[216:217], s[52:53], 0, v[134:135]
	global_load_lds_dwordx4 v[140:141], off
	v_lshl_add_u64 v[140:141], s[88:89], 0, v[128:129]
	s_mov_b32 m0, s80
	v_lshl_add_u64 v[218:219], s[52:53], 0, v[130:131]
	global_load_lds_dwordx4 v[140:141], off
	v_lshl_add_u64 v[140:141], v[216:217], 0, s[20:21]
	s_mov_b32 m0, s43
	s_nop 0
	global_load_lds_dwordx4 v[140:141], off
	v_lshl_add_u64 v[140:141], v[218:219], 0, s[20:21]
	s_mov_b32 m0, s61
	s_nop 0
	global_load_lds_dwordx4 v[140:141], off
	s_cmp_eq_u32 s99, 1
	s_cbranch_scc1 .Lrw_P3b_1
	s_waitcnt vmcnt(8)
	s_branch .Lrj_P3b_1

; #define PG8_STAGE(bufoff, gbase, voff) do { _Pragma("unroll") for (int _i = 0; _i < 2; ++_i) \
;         __builtin_amdgcn_global_load_lds((const unsigned*)((const char*)(gbase) + (voff)[_i]), (PG8_LAS unsigned*)(lds + (bufoff) + ldsw + _i * 8192), 16, 0, 0); } while (0)
; #define PG8_LDA(dst, b, h) do { _Pragma("unroll") for (int m = 0; m < 4; ++m) _Pragma("unroll") for (int k = 0; k < 2; ++k) dst[m][k] = *(const PG8_LAS bf16x8*)(lds + PG8_SA(b, h) + aoff + m * 2048 + k * 1024); } while (0)
; #define PG8_LDB(dst, b, h) do { _Pragma("unroll") for (int n = 0; n < 2; ++n) _Pragma("unroll") for (int k = 0; k < 2; ++k) dst[n][k] = *(const PG8_LAS bf16x8*)(lds + PG8_SB(b, h) + boff + n * 2048 + k * 1024); } while (0)
; #define PG8_MMA(ai, bj, At, Bt) do { __builtin_amdgcn_s_setprio(1); _Pragma("unroll") for (int m = 0; m < 4; ++m) _Pragma("unroll") for (int n = 0; n < 2; ++n) _Pragma("unroll") for (int k = 0; k < 2; ++k) \
;         acc[ai][bj][m][n] = __builtin_amdgcn_mfma_f32_16x16x32_bf16(Bt[n][k], At[m][k], acc[ai][bj][m][n], 0, 0, 0); __builtin_amdgcn_s_setprio(0); } while (0)
; #define PG8_WAIT_V(n) asm volatile("s_waitcnt vmcnt(" #n ")" ::: "memory")
; #define PG8_WAIT_L(n) asm volatile("s_waitcnt lgkmcnt(" #n ")" ::: "memory")
; #define PG8_BAR __builtin_amdgcn_s_barrier()
; #define PG8_SCHED __builtin_amdgcn_sched_barrier(0)
; template <class Epi, class Sched, bool ALIGN_EPI = false, bool SP2 = false>
; __device__ __forceinline__ void gemm_phase(PG8_LAS unsigned char* lds, const Gemm g, const Sched& S, const Epi& E) {
;     ...
;             PG8_WAIT_V(8); PG8_WAIT_L(0); PG8_BAR; PG8_MMA(1, 0, At, B0); PG8_MMA(1, 1, At, B1); PG8_BAR; PG8_SCHED;
;             PG8_LDB(B0, 1, 0); PG8_LDB(B1, 1, 1); PG8_SCHED; PG8_LDA(At, 1, 0); PG8_STAGE(PG8_SA(0, 1), a2 + hstep, voffA);
;             PG8_WAIT_V(8); PG8_WAIT_L(0); PG8_BAR; PG8_MMA(0, 0, At, B0); PG8_MMA(0, 1, At, B1); PG8_BAR; PG8_SCHED;
.Lrj_P3b_1:
	s_mov_b32 s99, 0
	s_waitcnt lgkmcnt(0)
	s_barrier
	s_setprio 1
	s_waitcnt lgkmcnt(0)
	v_mfma_f32_16x16x32_bf16 v[140:143], v[0:3], v[60:63], 0
	v_mfma_f32_16x16x32_bf16 v[158:161], v[0:3], v[104:107], 0
	v_mfma_f32_16x16x32_bf16 v[166:169], v[0:3], v[112:115], 0
	v_mfma_f32_16x16x32_bf16 v[0:3], v[0:3], v[120:123], 0
	v_mfma_f32_16x16x32_bf16 v[140:143], v[4:7], v[100:103], v[140:143]
	v_mfma_f32_16x16x32_bf16 v[158:161], v[4:7], v[108:111], v[158:161]
	v_mfma_f32_16x16x32_bf16 v[166:169], v[4:7], v[116:119], v[166:169]
	v_mfma_f32_16x16x32_bf16 v[0:3], v[4:7], v[124:127], v[0:3]
	v_mfma_f32_16x16x32_bf16 v[4:7], v[8:11], v[120:123], 0
	v_mfma_f32_16x16x32_bf16 v[154:157], v[8:11], v[60:63], 0
	v_mfma_f32_16x16x32_bf16 v[162:165], v[8:11], v[104:107], 0
	v_mfma_f32_16x16x32_bf16 v[170:173], v[8:11], v[112:115], 0
	v_mfma_f32_16x16x32_bf16 v[4:7], v[12:15], v[124:127], v[4:7]
	v_mfma_f32_16x16x32_bf16 v[154:157], v[12:15], v[100:103], v[154:157]
	v_mfma_f32_16x16x32_bf16 v[162:165], v[12:15], v[108:111], v[162:165]
	v_mfma_f32_16x16x32_bf16 v[170:173], v[12:15], v[116:119], v[170:173]
	v_mfma_f32_16x16x32_bf16 v[8:11], v[16:19], v[60:63], 0
	v_mfma_f32_16x16x32_bf16 v[12:15], v[24:27], v[60:63], 0
	v_mfma_f32_16x16x32_bf16 v[8:11], v[20:23], v[100:103], v[8:11]
	v_mfma_f32_16x16x32_bf16 v[12:15], v[28:31], v[100:103], v[12:15]
	v_mfma_f32_16x16x32_bf16 v[60:63], v[16:19], v[104:107], 0
	v_mfma_f32_16x16x32_bf16 v[100:103], v[24:27], v[104:107], 0
	v_mfma_f32_16x16x32_bf16 v[104:107], v[16:19], v[112:115], 0
	v_mfma_f32_16x16x32_bf16 v[16:19], v[16:19], v[120:123], 0
	v_mfma_f32_16x16x32_bf16 v[60:63], v[20:23], v[108:111], v[60:63]
	v_mfma_f32_16x16x32_bf16 v[100:103], v[28:31], v[108:111], v[100:103]
	v_mfma_f32_16x16x32_bf16 v[104:107], v[20:23], v[116:119], v[104:107]
	v_mfma_f32_16x16x32_bf16 v[108:111], v[24:27], v[112:115], 0
	v_mfma_f32_16x16x32_bf16 v[16:19], v[20:23], v[124:127], v[16:19]
	v_mfma_f32_16x16x32_bf16 v[20:23], v[24:27], v[120:123], 0
	v_mfma_f32_16x16x32_bf16 v[108:111], v[28:31], v[116:119], v[108:111]
	v_mfma_f32_16x16x32_bf16 v[20:23], v[28:31], v[124:127], v[20:23]
	s_setprio 0
	s_barrier
	s_add_i32 s37, 0, 0x1c000
	v_add_u32_e32 v153, s37, v147
	ds_read_b128 v[24:27], v152
	ds_read_b128 v[28:31], v152 offset:1024
	ds_read_b128 v[112:115], v152 offset:2048
	ds_read_b128 v[116:119], v152 offset:3072
	ds_read_b128 v[120:123], v153
	ds_read_b128 v[124:127], v153 offset:1024
	ds_read_b128 v[174:177], v153 offset:2048
	ds_read_b128 v[178:181], v153 offset:3072
	s_add_u32 s88, s52, 0x10100
	s_addc_u32 s89, s53, 0
	s_mov_b32 m0, s68
	v_lshl_add_u64 v[220:221], s[88:89], 0, v[134:135]
	ds_read_b128 v[182:185], v151 offset:32768
	ds_read_b128 v[186:189], v151 offset:33792
	ds_read_b128 v[190:193], v151 offset:34816
	ds_read_b128 v[194:197], v151 offset:35840
	ds_read_b128 v[198:201], v151 offset:36864
	ds_read_b128 v[202:205], v151 offset:37888
	ds_read_b128 v[206:209], v151 offset:38912
	ds_read_b128 v[210:213], v151 offset:39936
	global_load_lds_dwordx4 v[220:221], off
	v_lshl_add_u64 v[220:221], s[88:89], 0, v[130:131]
	s_mov_b32 m0, s69
	s_nop 0
	global_load_lds_dwordx4 v[220:221], off
	s_waitcnt vmcnt(8)
	s_waitcnt lgkmcnt(0)
	s_barrier
	s_setprio 1
	s_waitcnt lgkmcnt(0)
	v_mfma_f32_16x16x32_bf16 v[64:67], v[24:27], v[182:185], v[64:67]
	v_mfma_f32_16x16x32_bf16 v[68:71], v[112:115], v[182:185], v[68:71]
	v_mfma_f32_16x16x32_bf16 v[72:75], v[24:27], v[190:193], v[72:75]
	v_mfma_f32_16x16x32_bf16 v[76:79], v[112:115], v[190:193], v[76:79]
	v_mfma_f32_16x16x32_bf16 v[80:83], v[24:27], v[198:201], v[80:83]
	v_mfma_f32_16x16x32_bf16 v[84:87], v[112:115], v[198:201], v[84:87]
	v_mfma_f32_16x16x32_bf16 v[88:91], v[24:27], v[206:209], v[88:91]
	v_mfma_f32_16x16x32_bf16 v[92:95], v[112:115], v[206:209], v[92:95]
	v_mfma_f32_16x16x32_bf16 v[64:67], v[28:31], v[186:189], v[64:67]
	v_mfma_f32_16x16x32_bf16 v[68:71], v[116:119], v[186:189], v[68:71]
	v_mfma_f32_16x16x32_bf16 v[72:75], v[28:31], v[194:197], v[72:75]
	v_mfma_f32_16x16x32_bf16 v[76:79], v[116:119], v[194:197], v[76:79]
	v_mfma_f32_16x16x32_bf16 v[80:83], v[28:31], v[202:205], v[80:83]
	v_mfma_f32_16x16x32_bf16 v[84:87], v[116:119], v[202:205], v[84:87]
	v_mfma_f32_16x16x32_bf16 v[88:91], v[28:31], v[210:213], v[88:91]
	v_mfma_f32_16x16x32_bf16 v[92:95], v[116:119], v[210:213], v[92:95]
	v_mfma_f32_16x16x32_bf16 v[96:99], v[120:123], v[182:185], v[96:99]
	v_mfma_f32_16x16x32_bf16 v[32:35], v[174:177], v[182:185], v[32:35]
	v_mfma_f32_16x16x32_bf16 v[36:39], v[120:123], v[190:193], v[36:39]
	v_mfma_f32_16x16x32_bf16 v[40:43], v[174:177], v[190:193], v[40:43]
	v_mfma_f32_16x16x32_bf16 v[44:47], v[120:123], v[198:201], v[44:47]
	v_mfma_f32_16x16x32_bf16 v[48:51], v[174:177], v[198:201], v[48:51]
	v_mfma_f32_16x16x32_bf16 v[52:55], v[120:123], v[206:209], v[52:55]
	v_mfma_f32_16x16x32_bf16 v[56:59], v[174:177], v[206:209], v[56:59]
	v_mfma_f32_16x16x32_bf16 v[96:99], v[124:127], v[186:189], v[96:99]
	v_mfma_f32_16x16x32_bf16 v[32:35], v[178:181], v[186:189], v[32:35]
	v_mfma_f32_16x16x32_bf16 v[36:39], v[124:127], v[194:197], v[36:39]
	v_mfma_f32_16x16x32_bf16 v[40:43], v[178:181], v[194:197], v[40:43]
	v_mfma_f32_16x16x32_bf16 v[44:47], v[124:127], v[202:205], v[44:47]
	v_mfma_f32_16x16x32_bf16 v[48:51], v[178:181], v[202:205], v[48:51]
	v_mfma_f32_16x16x32_bf16 v[52:55], v[124:127], v[210:213], v[52:55]
	v_mfma_f32_16x16x32_bf16 v[56:59], v[178:181], v[210:213], v[56:59]
	s_setprio 0
	s_barrier
; #define PG8_STAGE(bufoff, gbase, voff) do { _Pragma("unroll") for (int _i = 0; _i < 2; ++_i) \
;         __builtin_amdgcn_global_load_lds((const unsigned*)((const char*)(gbase) + (voff)[_i]), (PG8_LAS unsigned*)(lds + (bufoff) + ldsw + _i * 8192), 16, 0, 0); } while (0)
; #define PG8_LDA(dst, b, h) do { _Pragma("unroll") for (int m = 0; m < 4; ++m) _Pragma("unroll") for (int k = 0; k < 2; ++k) dst[m][k] = *(const PG8_LAS bf16x8*)(lds + PG8_SA(b, h) + aoff + m * 2048 + k * 1024); } while (0)
; #define PG8_LDB(dst, b, h) do { _Pragma("unroll") for (int n = 0; n < 2; ++n) _Pragma("unroll") for (int k = 0; k < 2; ++k) dst[n][k] = *(const PG8_LAS bf16x8*)(lds + PG8_SB(b, h) + boff + n * 2048 + k * 1024); } while (0)
; #define PG8_MMA(ai, bj, At, Bt) do { __builtin_amdgcn_s_setprio(1); _Pragma("unroll") for (int m = 0; m < 4; ++m) _Pragma("unroll") for (int n = 0; n < 2; ++n) _Pragma("unroll") for (int k = 0; k < 2; ++k) \
;         acc[ai][bj][m][n] = __builtin_amdgcn_mfma_f32_16x16x32_bf16(Bt[n][k], At[m][k], acc[ai][bj][m][n], 0, 0, 0); __builtin_amdgcn_s_setprio(0); } while (0)
; #define PG8_WAIT_V(n) asm volatile("s_waitcnt vmcnt(" #n ")" ::: "memory")
; #define PG8_WAIT_L(n) asm volatile("s_waitcnt lgkmcnt(" #n ")" ::: "memory")
; #define PG8_BAR __builtin_amdgcn_s_barrier()
; #define PG8_SCHED __builtin_amdgcn_sched_barrier(0)
; template <class Epi, class Sched, bool ALIGN_EPI = false, bool SP2 = false>
; __device__ __forceinline__ void gemm_phase(PG8_LAS unsigned char* lds, const Gemm g, const Sched& S, const Epi& E) {
;     ...
;             PG8_LDB(B0, 0, 0); PG8_LDB(B1, 0, 1); PG8_SCHED; PG8_LDA(At, 0, 0); PG8_STAGE(PG8_SA(1, 1), a1 + hstep, voffA);
;             PG8_WAIT_V(8); PG8_WAIT_L(0); PG8_BAR; PG8_MMA(0, 0, At, B0); PG8_MMA(0, 1, At, B1); PG8_BAR; PG8_SCHED;
;     ...
;             PG8_LDA(At, 1, 1); PG8_STAGE(PG8_SB(1, 0), b3, voffB); PG8_STAGE(PG8_SB(1, 1), b3 + hstep, voffB); PG8_STAGE(PG8_SA(1, 0), a3, voffA);
;             PG8_WAIT_V(8); PG8_WAIT_L(0); PG8_BAR; PG8_MMA(1, 0, At, B0); PG8_MMA(1, 1, At, B1); PG8_BAR; PG8_SCHED;
	s_add_i32 s83, s81, s47
	s_add_i32 s35, s83, 0x2000
	v_lshl_add_u64 v[144:145], v[144:145], 0, s[22:23]
	s_mov_b32 m0, s83
	s_add_u32 s62, s62, 0x10180
	ds_read_b128 v[182:185], v151 offset:49152
	ds_read_b128 v[186:189], v151 offset:50176
	ds_read_b128 v[190:193], v151 offset:51200
	ds_read_b128 v[194:197], v151 offset:52224
	ds_read_b128 v[198:201], v151 offset:53248
	ds_read_b128 v[202:205], v151 offset:54272
	ds_read_b128 v[206:209], v151 offset:55296
	ds_read_b128 v[210:213], v151 offset:56320
	global_load_lds_dwordx4 v[144:145], off
	v_lshl_add_u64 v[144:145], v[214:215], 0, s[22:23]
	s_mov_b32 m0, s35
	s_addc_u32 s63, s63, 0
	s_add_i32 s37, s37, s47
	global_load_lds_dwordx4 v[144:145], off
	v_lshl_add_u64 v[144:145], s[62:63], 0, v[132:133]
	s_mov_b32 m0, s37
	s_nop 0
	global_load_lds_dwordx4 v[144:145], off
	v_lshl_add_u64 v[144:145], s[62:63], 0, v[128:129]
	s_add_i32 s62, s37, 0x2000
	s_mov_b32 m0, s62
	s_nop 0
	global_load_lds_dwordx4 v[144:145], off
	v_lshl_add_u64 v[144:145], v[216:217], 0, s[22:23]
	s_mov_b32 m0, s70
	s_nop 0
	global_load_lds_dwordx4 v[144:145], off
	v_lshl_add_u64 v[144:145], v[218:219], 0, s[22:23]
	s_mov_b32 m0, s71
	s_nop 0
	global_load_lds_dwordx4 v[144:145], off
	s_waitcnt vmcnt(8)
	s_waitcnt lgkmcnt(0)
	s_barrier
	s_setprio 1
	s_waitcnt lgkmcnt(0)
	v_mfma_f32_16x16x32_bf16 v[0:3], v[24:27], v[206:209], v[0:3]
	v_mfma_f32_16x16x32_bf16 v[4:7], v[112:115], v[206:209], v[4:7]
	v_mfma_f32_16x16x32_bf16 v[140:143], v[24:27], v[182:185], v[140:143]
	v_mfma_f32_16x16x32_bf16 v[154:157], v[112:115], v[182:185], v[154:157]
	v_mfma_f32_16x16x32_bf16 v[158:161], v[24:27], v[190:193], v[158:161]
	v_mfma_f32_16x16x32_bf16 v[162:165], v[112:115], v[190:193], v[162:165]
	v_mfma_f32_16x16x32_bf16 v[166:169], v[24:27], v[198:201], v[166:169]
	v_mfma_f32_16x16x32_bf16 v[170:173], v[112:115], v[198:201], v[170:173]
	v_mfma_f32_16x16x32_bf16 v[0:3], v[28:31], v[210:213], v[0:3]
	v_mfma_f32_16x16x32_bf16 v[4:7], v[116:119], v[210:213], v[4:7]
	v_mfma_f32_16x16x32_bf16 v[140:143], v[28:31], v[186:189], v[140:143]
	v_mfma_f32_16x16x32_bf16 v[154:157], v[116:119], v[186:189], v[154:157]
	v_mfma_f32_16x16x32_bf16 v[158:161], v[28:31], v[194:197], v[158:161]
	v_mfma_f32_16x16x32_bf16 v[162:165], v[116:119], v[194:197], v[162:165]
	v_mfma_f32_16x16x32_bf16 v[166:169], v[28:31], v[202:205], v[166:169]
	v_mfma_f32_16x16x32_bf16 v[170:173], v[116:119], v[202:205], v[170:173]
	v_mfma_f32_16x16x32_bf16 v[8:11], v[120:123], v[182:185], v[8:11]
	v_mfma_f32_16x16x32_bf16 v[12:15], v[174:177], v[182:185], v[12:15]
	v_mfma_f32_16x16x32_bf16 v[24:27], v[120:123], v[190:193], v[60:63]
	v_mfma_f32_16x16x32_bf16 v[28:31], v[174:177], v[190:193], v[100:103]
	v_mfma_f32_16x16x32_bf16 v[60:63], v[120:123], v[198:201], v[104:107]
	v_mfma_f32_16x16x32_bf16 v[100:103], v[174:177], v[198:201], v[108:111]
	v_mfma_f32_16x16x32_bf16 v[16:19], v[120:123], v[206:209], v[16:19]
	v_mfma_f32_16x16x32_bf16 v[20:23], v[174:177], v[206:209], v[20:23]
	v_mfma_f32_16x16x32_bf16 v[8:11], v[124:127], v[186:189], v[8:11]
	v_mfma_f32_16x16x32_bf16 v[12:15], v[178:181], v[186:189], v[12:15]
	v_mfma_f32_16x16x32_bf16 v[24:27], v[124:127], v[194:197], v[24:27]
	v_mfma_f32_16x16x32_bf16 v[28:31], v[178:181], v[194:197], v[28:31]
	v_mfma_f32_16x16x32_bf16 v[60:63], v[124:127], v[202:205], v[60:63]
	v_mfma_f32_16x16x32_bf16 v[100:103], v[178:181], v[202:205], v[100:103]
	v_mfma_f32_16x16x32_bf16 v[16:19], v[124:127], v[210:213], v[16:19]
	v_mfma_f32_16x16x32_bf16 v[20:23], v[178:181], v[210:213], v[20:23]
	s_setprio 0
	s_barrier
	ds_read_b128 v[104:107], v149
	ds_read_b128 v[108:111], v149 offset:1024
	ds_read_b128 v[112:115], v149 offset:2048
	ds_read_b128 v[116:119], v149 offset:3072
	ds_read_b128 v[120:123], v150
	ds_read_b128 v[124:127], v150 offset:1024
	ds_read_b128 v[174:177], v150 offset:2048
	ds_read_b128 v[178:181], v150 offset:3072
	s_add_u32 s52, s52, 0x10180
	s_addc_u32 s53, s53, 0
	s_mov_b32 m0, s73
	v_lshl_add_u64 v[144:145], s[52:53], 0, v[134:135]
	ds_read_b128 v[182:185], v151
	ds_read_b128 v[186:189], v151 offset:1024
	ds_read_b128 v[190:193], v151 offset:2048
	ds_read_b128 v[194:197], v151 offset:3072
	ds_read_b128 v[198:201], v151 offset:4096
	ds_read_b128 v[202:205], v151 offset:5120
	ds_read_b128 v[206:209], v151 offset:6144
	ds_read_b128 v[210:213], v151 offset:7168
	global_load_lds_dwordx4 v[144:145], off
	v_lshl_add_u64 v[144:145], s[52:53], 0, v[130:131]
	s_mov_b32 m0, s74
	s_nop 0
	global_load_lds_dwordx4 v[144:145], off
	s_waitcnt vmcnt(8)
	s_waitcnt lgkmcnt(0)
	s_barrier
; #define PG8_STAGE(bufoff, gbase, voff) do { _Pragma("unroll") for (int _i = 0; _i < 2; ++_i) \
;         __builtin_amdgcn_global_load_lds((const unsigned*)((const char*)(gbase) + (voff)[_i]), (PG8_LAS unsigned*)(lds + (bufoff) + ldsw + _i * 8192), 16, 0, 0); } while (0)
; #define PG8_LDA(dst, b, h) do { _Pragma("unroll") for (int m = 0; m < 4; ++m) _Pragma("unroll") for (int k = 0; k < 2; ++k) dst[m][k] = *(const PG8_LAS bf16x8*)(lds + PG8_SA(b, h) + aoff + m * 2048 + k * 1024); } while (0)
; #define PG8_MMA(ai, bj, At, Bt) do { __builtin_amdgcn_s_setprio(1); _Pragma("unroll") for (int m = 0; m < 4; ++m) _Pragma("unroll") for (int n = 0; n < 2; ++n) _Pragma("unroll") for (int k = 0; k < 2; ++k) \
;         acc[ai][bj][m][n] = __builtin_amdgcn_mfma_f32_16x16x32_bf16(Bt[n][k], At[m][k], acc[ai][bj][m][n], 0, 0, 0); __builtin_amdgcn_s_setprio(0); } while (0)
; #define PG8_WAIT_V(n) asm volatile("s_waitcnt vmcnt(" #n ")" ::: "memory")
; #define PG8_WAIT_L(n) asm volatile("s_waitcnt lgkmcnt(" #n ")" ::: "memory")
; #define PG8_BAR __builtin_amdgcn_s_barrier()
; #define PG8_SCHED __builtin_amdgcn_sched_barrier(0)
; template <class Epi, class Sched, bool ALIGN_EPI = false, bool SP2 = false>
; __device__ __forceinline__ void gemm_phase(PG8_LAS unsigned char* lds, const Gemm g, const Sched& S, const Epi& E) {
;     ...
;             PG8_WAIT_V(8); PG8_WAIT_L(0); PG8_BAR; PG8_MMA(0, 0, At, B0); PG8_MMA(0, 1, At, B1); PG8_BAR; PG8_SCHED;
;             PG8_LDA(At, 0, 1); PG8_STAGE(PG8_SB(0, 0), b2, voffB); PG8_STAGE(PG8_SB(0, 1), b2 + hstep, voffB); PG8_STAGE(PG8_SA(0, 0), a2, voffA);
;             PG8_WAIT_V(8); PG8_WAIT_L(0); PG8_BAR; PG8_MMA(1, 0, At, B0); PG8_MMA(1, 1, At, B1); PG8_BAR; PG8_SCHED;
	s_setprio 1
	s_waitcnt lgkmcnt(0)
	v_mfma_f32_16x16x32_bf16 v[64:67], v[104:107], v[182:185], v[64:67]
	v_mfma_f32_16x16x32_bf16 v[68:71], v[112:115], v[182:185], v[68:71]
	v_mfma_f32_16x16x32_bf16 v[72:75], v[104:107], v[190:193], v[72:75]
	v_mfma_f32_16x16x32_bf16 v[76:79], v[112:115], v[190:193], v[76:79]
	v_mfma_f32_16x16x32_bf16 v[80:83], v[104:107], v[198:201], v[80:83]
	v_mfma_f32_16x16x32_bf16 v[84:87], v[112:115], v[198:201], v[84:87]
	v_mfma_f32_16x16x32_bf16 v[88:91], v[104:107], v[206:209], v[88:91]
	v_mfma_f32_16x16x32_bf16 v[64:67], v[108:111], v[186:189], v[64:67]
	v_mfma_f32_16x16x32_bf16 v[68:71], v[116:119], v[186:189], v[68:71]
	v_mfma_f32_16x16x32_bf16 v[72:75], v[108:111], v[194:197], v[72:75]
	v_mfma_f32_16x16x32_bf16 v[76:79], v[116:119], v[194:197], v[76:79]
	v_mfma_f32_16x16x32_bf16 v[80:83], v[108:111], v[202:205], v[80:83]
	v_mfma_f32_16x16x32_bf16 v[84:87], v[116:119], v[202:205], v[84:87]
	v_mfma_f32_16x16x32_bf16 v[214:217], v[108:111], v[210:213], v[88:91]
	v_mfma_f32_16x16x32_bf16 v[88:91], v[112:115], v[206:209], v[92:95]
	v_mfma_f32_16x16x32_bf16 v[218:221], v[116:119], v[210:213], v[88:91]
	v_mfma_f32_16x16x32_bf16 v[88:91], v[120:123], v[182:185], v[96:99]
	v_mfma_f32_16x16x32_bf16 v[32:35], v[174:177], v[182:185], v[32:35]
	v_mfma_f32_16x16x32_bf16 v[36:39], v[120:123], v[190:193], v[36:39]
	v_mfma_f32_16x16x32_bf16 v[40:43], v[174:177], v[190:193], v[40:43]
	v_mfma_f32_16x16x32_bf16 v[44:47], v[120:123], v[198:201], v[44:47]
	v_mfma_f32_16x16x32_bf16 v[48:51], v[174:177], v[198:201], v[48:51]
	v_mfma_f32_16x16x32_bf16 v[52:55], v[120:123], v[206:209], v[52:55]
	v_mfma_f32_16x16x32_bf16 v[56:59], v[174:177], v[206:209], v[56:59]
	v_mfma_f32_16x16x32_bf16 v[96:99], v[124:127], v[186:189], v[88:91]
	v_mfma_f32_16x16x32_bf16 v[32:35], v[178:181], v[186:189], v[32:35]
	v_mfma_f32_16x16x32_bf16 v[36:39], v[124:127], v[194:197], v[36:39]
	v_mfma_f32_16x16x32_bf16 v[40:43], v[178:181], v[194:197], v[40:43]
	v_mfma_f32_16x16x32_bf16 v[44:47], v[124:127], v[202:205], v[44:47]
	v_mfma_f32_16x16x32_bf16 v[48:51], v[178:181], v[202:205], v[48:51]
	v_mfma_f32_16x16x32_bf16 v[52:55], v[124:127], v[210:213], v[52:55]
	v_mfma_f32_16x16x32_bf16 v[56:59], v[178:181], v[210:213], v[56:59]
	s_setprio 0
	s_barrier
	s_mov_b32 m0, s75
	v_lshl_add_u64 v[144:145], s[64:65], 0, v[132:133]
	s_add_u32 s52, s64, 0x10000
	ds_read_b128 v[88:91], v151 offset:16384
	ds_read_b128 v[92:95], v151 offset:17408
	ds_read_b128 v[182:185], v151 offset:18432
	ds_read_b128 v[186:189], v151 offset:19456
	ds_read_b128 v[190:193], v151 offset:20480
	ds_read_b128 v[194:197], v151 offset:21504
	ds_read_b128 v[198:201], v151 offset:22528
	ds_read_b128 v[202:205], v151 offset:23552
	global_load_lds_dwordx4 v[144:145], off
	v_lshl_add_u64 v[248:249], s[64:65], 0, v[128:129]
	s_mov_b32 m0, s76
	s_addc_u32 s53, s65, 0
	global_load_lds_dwordx4 v[248:249], off
	v_lshl_add_u64 v[206:207], s[52:53], 0, v[132:133]
	s_mov_b32 m0, s77
	v_lshl_add_u64 v[250:251], s[66:67], 0, v[134:135]
	global_load_lds_dwordx4 v[206:207], off
	v_lshl_add_u64 v[206:207], s[52:53], 0, v[128:129]
	s_mov_b32 m0, s80
	v_lshl_add_u64 v[252:253], s[66:67], 0, v[130:131]
	global_load_lds_dwordx4 v[206:207], off
	s_mov_b32 m0, s43
	s_nop 0
	global_load_lds_dwordx4 v[250:251], off
	s_mov_b32 m0, s61
	s_nop 0
	global_load_lds_dwordx4 v[252:253], off
	s_waitcnt vmcnt(8)
	s_waitcnt lgkmcnt(0)
	s_barrier
	s_setprio 1
	s_waitcnt lgkmcnt(0)
	v_mfma_f32_16x16x32_bf16 v[0:3], v[104:107], v[198:201], v[0:3]
	v_mfma_f32_16x16x32_bf16 v[4:7], v[112:115], v[198:201], v[4:7]
	v_mfma_f32_16x16x32_bf16 v[140:143], v[104:107], v[88:91], v[140:143]
	v_mfma_f32_16x16x32_bf16 v[154:157], v[112:115], v[88:91], v[154:157]
	v_mfma_f32_16x16x32_bf16 v[158:161], v[104:107], v[182:185], v[158:161]
	v_mfma_f32_16x16x32_bf16 v[162:165], v[112:115], v[182:185], v[162:165]
	v_mfma_f32_16x16x32_bf16 v[166:169], v[104:107], v[190:193], v[166:169]
	v_mfma_f32_16x16x32_bf16 v[170:173], v[112:115], v[190:193], v[170:173]
	v_mfma_f32_16x16x32_bf16 v[0:3], v[108:111], v[202:205], v[0:3]
	v_mfma_f32_16x16x32_bf16 v[4:7], v[116:119], v[202:205], v[4:7]
	v_mfma_f32_16x16x32_bf16 v[140:143], v[108:111], v[92:95], v[140:143]
	v_mfma_f32_16x16x32_bf16 v[154:157], v[116:119], v[92:95], v[154:157]
	v_mfma_f32_16x16x32_bf16 v[158:161], v[108:111], v[186:189], v[158:161]
	v_mfma_f32_16x16x32_bf16 v[162:165], v[116:119], v[186:189], v[162:165]
	v_mfma_f32_16x16x32_bf16 v[166:169], v[108:111], v[194:197], v[166:169]
	v_mfma_f32_16x16x32_bf16 v[170:173], v[116:119], v[194:197], v[170:173]
	v_mfma_f32_16x16x32_bf16 v[8:11], v[120:123], v[88:91], v[8:11]
	v_mfma_f32_16x16x32_bf16 v[206:209], v[124:127], v[92:95], v[8:11]
	v_mfma_f32_16x16x32_bf16 v[8:11], v[174:177], v[88:91], v[12:15]
	v_mfma_f32_16x16x32_bf16 v[210:213], v[178:181], v[92:95], v[8:11]
	v_mfma_f32_16x16x32_bf16 v[8:11], v[120:123], v[182:185], v[24:27]
	v_mfma_f32_16x16x32_bf16 v[222:225], v[124:127], v[186:189], v[8:11]
	v_mfma_f32_16x16x32_bf16 v[8:11], v[174:177], v[182:185], v[28:31]
	v_mfma_f32_16x16x32_bf16 v[182:185], v[178:181], v[186:189], v[8:11]
	v_mfma_f32_16x16x32_bf16 v[8:11], v[120:123], v[190:193], v[60:63]
	v_mfma_f32_16x16x32_bf16 v[186:189], v[124:127], v[194:197], v[8:11]
	v_mfma_f32_16x16x32_bf16 v[8:11], v[174:177], v[190:193], v[100:103]
	v_mfma_f32_16x16x32_bf16 v[190:193], v[178:181], v[194:197], v[8:11]
	v_mfma_f32_16x16x32_bf16 v[8:11], v[120:123], v[198:201], v[16:19]
	v_mfma_f32_16x16x32_bf16 v[194:197], v[124:127], v[202:205], v[8:11]
	v_mfma_f32_16x16x32_bf16 v[8:11], v[174:177], v[198:201], v[20:23]
	v_mfma_f32_16x16x32_bf16 v[174:177], v[178:181], v[202:205], v[8:11]
	s_setprio 0
	s_barrier
; #define PG8_STAGE(bufoff, gbase, voff) do { _Pragma("unroll") for (int _i = 0; _i < 2; ++_i) \
;         __builtin_amdgcn_global_load_lds((const unsigned*)((const char*)(gbase) + (voff)[_i]), (PG8_LAS unsigned*)(lds + (bufoff) + ldsw + _i * 8192), 16, 0, 0); } while (0)
; #define PG8_LDA(dst, b, h) do { _Pragma("unroll") for (int m = 0; m < 4; ++m) _Pragma("unroll") for (int k = 0; k < 2; ++k) dst[m][k] = *(const PG8_LAS bf16x8*)(lds + PG8_SA(b, h) + aoff + m * 2048 + k * 1024); } while (0)
; #define PG8_LDB(dst, b, h) do { _Pragma("unroll") for (int n = 0; n < 2; ++n) _Pragma("unroll") for (int k = 0; k < 2; ++k) dst[n][k] = *(const PG8_LAS bf16x8*)(lds + PG8_SB(b, h) + boff + n * 2048 + k * 1024); } while (0)
; #define PG8_MMA(ai, bj, At, Bt) do { __builtin_amdgcn_s_setprio(1); _Pragma("unroll") for (int m = 0; m < 4; ++m) _Pragma("unroll") for (int n = 0; n < 2; ++n) _Pragma("unroll") for (int k = 0; k < 2; ++k) \
;         acc[ai][bj][m][n] = __builtin_amdgcn_mfma_f32_16x16x32_bf16(Bt[n][k], At[m][k], acc[ai][bj][m][n], 0, 0, 0); __builtin_amdgcn_s_setprio(0); } while (0)
; #define PG8_WAIT_V(n) asm volatile("s_waitcnt vmcnt(" #n ")" ::: "memory")
; #define PG8_WAIT_L(n) asm volatile("s_waitcnt lgkmcnt(" #n ")" ::: "memory")
; #define PG8_BAR __builtin_amdgcn_s_barrier()
; #define PG8_SCHED __builtin_amdgcn_sched_barrier(0)
; template <class Epi, class Sched, bool ALIGN_EPI = false, bool SP2 = false>
; __device__ __forceinline__ void gemm_phase(PG8_LAS unsigned char* lds, const Gemm g, const Sched& S, const Epi& E) {
;     ...
;             PG8_LDB(B0, 1, 0); PG8_LDB(B1, 1, 1); PG8_SCHED; PG8_LDA(At, 1, 0); PG8_STAGE(PG8_SA(0, 1), a2 + hstep, voffA);
;             PG8_WAIT_V(8); PG8_WAIT_L(0); PG8_BAR; PG8_MMA(0, 0, At, B0); PG8_MMA(0, 1, At, B1); PG8_BAR; PG8_SCHED;
;             PG8_LDA(At, 1, 1); PG8_STAGE(PG8_SB(1, 0), b3, voffB); PG8_STAGE(PG8_SB(1, 1), b3 + hstep, voffB); PG8_STAGE(PG8_SA(1, 0), a3, voffA);
;             PG8_WAIT_V(8); PG8_WAIT_L(0); PG8_BAR; PG8_MMA(1, 0, At, B0); PG8_MMA(1, 1, At, B1); PG8_BAR; PG8_SCHED;
;     ...
;         if constexpr (ALIGN_EPI) { if (wr == 0) PG8_BAR; }
	s_nop 4
	ds_read_b128 v[8:11], v152
	ds_read_b128 v[12:15], v152 offset:1024
	ds_read_b128 v[16:19], v152 offset:2048
	ds_read_b128 v[20:23], v152 offset:3072
	ds_read_b128 v[178:181], v153
	ds_read_b128 v[198:201], v153 offset:1024
	ds_read_b128 v[202:205], v153 offset:2048
	ds_read_b128 v[228:231], v153 offset:3072
	s_add_u32 s52, s66, 0x10000
	s_addc_u32 s53, s67, 0
	s_mov_b32 m0, s68
	v_lshl_add_u64 v[88:89], s[52:53], 0, v[134:135]
	ds_read_b128 v[24:27], v151 offset:32768
	ds_read_b128 v[28:31], v151 offset:33792
	ds_read_b128 v[60:63], v151 offset:34816
	ds_read_b128 v[100:103], v151 offset:35840
	ds_read_b128 v[232:235], v151 offset:36864
	ds_read_b128 v[236:239], v151 offset:37888
	ds_read_b128 v[240:243], v151 offset:38912
	ds_read_b128 v[244:247], v151 offset:39936
	global_load_lds_dwordx4 v[88:89], off
	v_lshl_add_u64 v[88:89], s[52:53], 0, v[130:131]
	s_mov_b32 m0, s69
	s_nop 0
	global_load_lds_dwordx4 v[88:89], off
	s_waitcnt vmcnt(8)
	s_waitcnt lgkmcnt(0)
	s_barrier
	s_setprio 1
	s_waitcnt lgkmcnt(0)
	v_mfma_f32_16x16x32_bf16 v[64:67], v[8:11], v[24:27], v[64:67]
	v_mfma_f32_16x16x32_bf16 v[124:127], v[12:15], v[28:31], v[64:67]
	v_mfma_f32_16x16x32_bf16 v[64:67], v[16:19], v[24:27], v[68:71]
	v_mfma_f32_16x16x32_bf16 v[120:123], v[20:23], v[28:31], v[64:67]
	v_mfma_f32_16x16x32_bf16 v[64:67], v[8:11], v[60:63], v[72:75]
	v_mfma_f32_16x16x32_bf16 v[108:111], v[12:15], v[100:103], v[64:67]
	v_mfma_f32_16x16x32_bf16 v[64:67], v[16:19], v[60:63], v[76:79]
	v_mfma_f32_16x16x32_bf16 v[104:107], v[20:23], v[100:103], v[64:67]
	v_mfma_f32_16x16x32_bf16 v[64:67], v[8:11], v[232:235], v[80:83]
	v_mfma_f32_16x16x32_bf16 v[92:95], v[12:15], v[236:239], v[64:67]
	v_mfma_f32_16x16x32_bf16 v[64:67], v[16:19], v[232:235], v[84:87]
	v_mfma_f32_16x16x32_bf16 v[88:91], v[20:23], v[236:239], v[64:67]
	v_mfma_f32_16x16x32_bf16 v[64:67], v[8:11], v[240:243], v[214:217]
	v_mfma_f32_16x16x32_bf16 v[76:79], v[12:15], v[244:247], v[64:67]
	v_mfma_f32_16x16x32_bf16 v[64:67], v[16:19], v[240:243], v[218:221]
	v_mfma_f32_16x16x32_bf16 v[72:75], v[20:23], v[244:247], v[64:67]
	v_mfma_f32_16x16x32_bf16 v[64:67], v[178:181], v[24:27], v[96:99]
	v_mfma_f32_16x16x32_bf16 v[24:27], v[202:205], v[24:27], v[32:35]
	v_mfma_f32_16x16x32_bf16 v[116:119], v[228:231], v[28:31], v[24:27]
	v_mfma_f32_16x16x32_bf16 v[24:27], v[178:181], v[60:63], v[36:39]
	v_mfma_f32_16x16x32_bf16 v[96:99], v[198:201], v[100:103], v[24:27]
	v_mfma_f32_16x16x32_bf16 v[24:27], v[202:205], v[60:63], v[40:43]
	v_mfma_f32_16x16x32_bf16 v[100:103], v[228:231], v[100:103], v[24:27]
	v_mfma_f32_16x16x32_bf16 v[24:27], v[178:181], v[232:235], v[44:47]
	v_mfma_f32_16x16x32_bf16 v[80:83], v[198:201], v[236:239], v[24:27]
	v_mfma_f32_16x16x32_bf16 v[24:27], v[202:205], v[232:235], v[48:51]
	v_mfma_f32_16x16x32_bf16 v[84:87], v[228:231], v[236:239], v[24:27]
	v_mfma_f32_16x16x32_bf16 v[24:27], v[178:181], v[240:243], v[52:55]
	v_mfma_f32_16x16x32_bf16 v[112:115], v[198:201], v[28:31], v[64:67]
	v_mfma_f32_16x16x32_bf16 v[64:67], v[198:201], v[244:247], v[24:27]
	v_mfma_f32_16x16x32_bf16 v[24:27], v[202:205], v[240:243], v[56:59]
	v_mfma_f32_16x16x32_bf16 v[68:71], v[228:231], v[244:247], v[24:27]
	s_setprio 0
	s_barrier
	s_mov_b32 m0, s83
	s_nop 3
	v_lshl_add_u64 v[24:25], v[144:145], 0, s[14:15]
	s_add_u32 s52, s64, 0x10080
	ds_read_b128 v[32:35], v151 offset:49152
	ds_read_b128 v[36:39], v151 offset:50176
	ds_read_b128 v[214:217], v151 offset:51200
	ds_read_b128 v[218:221], v151 offset:52224
	ds_read_b128 v[232:235], v151 offset:53248
	ds_read_b128 v[236:239], v151 offset:54272
	ds_read_b128 v[240:243], v151 offset:55296
	ds_read_b128 v[244:247], v151 offset:56320
	global_load_lds_dwordx4 v[24:25], off
	v_lshl_add_u64 v[24:25], v[248:249], 0, s[14:15]
	s_mov_b32 m0, s35
	s_addc_u32 s53, s65, 0
	global_load_lds_dwordx4 v[24:25], off
	v_lshl_add_u64 v[24:25], s[52:53], 0, v[132:133]
	s_mov_b32 m0, s37
	s_nop 0
	global_load_lds_dwordx4 v[24:25], off
	v_lshl_add_u64 v[24:25], s[52:53], 0, v[128:129]
	s_mov_b32 m0, s62
	s_nop 0
	global_load_lds_dwordx4 v[24:25], off
	v_lshl_add_u64 v[24:25], v[250:251], 0, s[14:15]
	s_mov_b32 m0, s70
	s_nop 0
	global_load_lds_dwordx4 v[24:25], off
	v_lshl_add_u64 v[24:25], v[252:253], 0, s[14:15]
	s_mov_b32 m0, s71
	s_nop 0
	global_load_lds_dwordx4 v[24:25], off
	s_waitcnt vmcnt(8)
	s_waitcnt lgkmcnt(0)
	s_barrier
	s_setprio 1
	s_waitcnt lgkmcnt(0)
	v_mfma_f32_16x16x32_bf16 v[24:27], v[8:11], v[32:35], v[140:143]
	v_mfma_f32_16x16x32_bf16 v[60:63], v[12:15], v[36:39], v[24:27]
	v_mfma_f32_16x16x32_bf16 v[24:27], v[16:19], v[32:35], v[154:157]
	v_mfma_f32_16x16x32_bf16 v[56:59], v[20:23], v[36:39], v[24:27]
	v_mfma_f32_16x16x32_bf16 v[24:27], v[8:11], v[214:217], v[158:161]
	v_mfma_f32_16x16x32_bf16 v[44:47], v[12:15], v[218:221], v[24:27]
	v_mfma_f32_16x16x32_bf16 v[24:27], v[16:19], v[214:217], v[162:165]
	v_mfma_f32_16x16x32_bf16 v[40:43], v[20:23], v[218:221], v[24:27]
	v_mfma_f32_16x16x32_bf16 v[24:27], v[8:11], v[232:235], v[166:169]
	v_mfma_f32_16x16x32_bf16 v[0:3], v[8:11], v[240:243], v[0:3]
	v_mfma_f32_16x16x32_bf16 v[28:31], v[12:15], v[236:239], v[24:27]
	v_mfma_f32_16x16x32_bf16 v[24:27], v[16:19], v[232:235], v[170:173]
	v_mfma_f32_16x16x32_bf16 v[12:15], v[12:15], v[244:247], v[0:3]
	v_mfma_f32_16x16x32_bf16 v[0:3], v[16:19], v[240:243], v[4:7]
	v_mfma_f32_16x16x32_bf16 v[24:27], v[20:23], v[236:239], v[24:27]
	v_mfma_f32_16x16x32_bf16 v[8:11], v[20:23], v[244:247], v[0:3]
	v_mfma_f32_16x16x32_bf16 v[0:3], v[178:181], v[32:35], v[206:209]
	v_mfma_f32_16x16x32_bf16 v[48:51], v[198:201], v[36:39], v[0:3]
	v_mfma_f32_16x16x32_bf16 v[0:3], v[202:205], v[32:35], v[210:213]
	v_mfma_f32_16x16x32_bf16 v[52:55], v[228:231], v[36:39], v[0:3]
	v_mfma_f32_16x16x32_bf16 v[0:3], v[178:181], v[214:217], v[222:225]
	v_mfma_f32_16x16x32_bf16 v[32:35], v[198:201], v[218:221], v[0:3]
	v_mfma_f32_16x16x32_bf16 v[0:3], v[202:205], v[214:217], v[182:185]
	v_mfma_f32_16x16x32_bf16 v[36:39], v[228:231], v[218:221], v[0:3]
	v_mfma_f32_16x16x32_bf16 v[0:3], v[178:181], v[232:235], v[186:189]
	v_mfma_f32_16x16x32_bf16 v[16:19], v[198:201], v[236:239], v[0:3]
	v_mfma_f32_16x16x32_bf16 v[0:3], v[202:205], v[232:235], v[190:193]
	v_mfma_f32_16x16x32_bf16 v[20:23], v[228:231], v[236:239], v[0:3]
	v_mfma_f32_16x16x32_bf16 v[0:3], v[178:181], v[240:243], v[194:197]
	v_mfma_f32_16x16x32_bf16 v[4:7], v[198:201], v[244:247], v[0:3]
	v_mfma_f32_16x16x32_bf16 v[0:3], v[202:205], v[240:243], v[174:177]
	v_mfma_f32_16x16x32_bf16 v[0:3], v[228:231], v[244:247], v[0:3]
	s_setprio 0
	s_barrier
	s_andn2_b64 vcc, exec, s[16:17]
	s_cbranch_vccnz .LBB0_1356
	s_barrier

; #define PG8_STAGE(bufoff, gbase, voff) do { _Pragma("unroll") for (int _i = 0; _i < 2; ++_i) \
;         __builtin_amdgcn_global_load_lds((const unsigned*)((const char*)(gbase) + (voff)[_i]), (PG8_LAS unsigned*)(lds + (bufoff) + ldsw + _i * 8192), 16, 0, 0); } while (0)
; #define PG8_LDA(dst, b, h) do { _Pragma("unroll") for (int m = 0; m < 4; ++m) _Pragma("unroll") for (int k = 0; k < 2; ++k) dst[m][k] = *(const PG8_LAS bf16x8*)(lds + PG8_SA(b, h) + aoff + m * 2048 + k * 1024); } while (0)
; #define PG8_MMA(ai, bj, At, Bt) do { __builtin_amdgcn_s_setprio(1); _Pragma("unroll") for (int m = 0; m < 4; ++m) _Pragma("unroll") for (int n = 0; n < 2; ++n) _Pragma("unroll") for (int k = 0; k < 2; ++k) \
;         acc[ai][bj][m][n] = __builtin_amdgcn_mfma_f32_16x16x32_bf16(Bt[n][k], At[m][k], acc[ai][bj][m][n], 0, 0, 0); __builtin_amdgcn_s_setprio(0); } while (0)
; #define PG8_WAIT_V(n) asm volatile("s_waitcnt vmcnt(" #n ")" ::: "memory")
; #define PG8_WAIT_L(n) asm volatile("s_waitcnt lgkmcnt(" #n ")" ::: "memory")
; #define PG8_BAR __builtin_amdgcn_s_barrier()
; #define PG8_SCHED __builtin_amdgcn_sched_barrier(0)
; template <class Epi, class Sched, bool ALIGN_EPI = false, bool SP2 = false>
; __device__ __forceinline__ void gemm_phase(PG8_LAS unsigned char* lds, const Gemm g, const Sched& S, const Epi& E) {
;     ...
;             PG8_WAIT_V(8); PG8_WAIT_L(0); PG8_BAR; PG8_MMA(0, 0, At, B0); PG8_MMA(0, 1, At, B1); PG8_BAR; PG8_SCHED;
;             PG8_LDA(At, 0, 1); PG8_STAGE(PG8_SB(0, 0), b2, voffB); PG8_STAGE(PG8_SB(0, 1), b2 + hstep, voffB); PG8_STAGE(PG8_SA(0, 0), a2, voffA);
.Lrj_P4_0:
	s_waitcnt lgkmcnt(0)
	s_barrier
	s_setprio 1
	s_waitcnt lgkmcnt(0)
	v_mfma_f32_16x16x32_bf16 v[140:143], v[56:59], v[186:189], v[140:143]
	v_mfma_f32_16x16x32_bf16 v[136:139], v[72:75], v[186:189], v[136:139]
	v_mfma_f32_16x16x32_bf16 v[124:127], v[56:59], v[194:197], v[124:127]
	v_mfma_f32_16x16x32_bf16 v[120:123], v[72:75], v[194:197], v[120:123]
	v_mfma_f32_16x16x32_bf16 v[108:111], v[56:59], v[202:205], v[108:111]
	v_mfma_f32_16x16x32_bf16 v[104:107], v[72:75], v[202:205], v[104:107]
	v_mfma_f32_16x16x32_bf16 v[92:95], v[56:59], v[210:213], v[92:95]
	v_mfma_f32_16x16x32_bf16 v[88:91], v[72:75], v[210:213], v[88:91]
	v_mfma_f32_16x16x32_bf16 v[140:143], v[60:63], v[190:193], v[140:143]
	v_mfma_f32_16x16x32_bf16 v[136:139], v[76:79], v[190:193], v[136:139]
	v_mfma_f32_16x16x32_bf16 v[124:127], v[60:63], v[198:201], v[124:127]
	v_mfma_f32_16x16x32_bf16 v[120:123], v[76:79], v[198:201], v[120:123]
	v_mfma_f32_16x16x32_bf16 v[108:111], v[60:63], v[206:209], v[108:111]
	v_mfma_f32_16x16x32_bf16 v[104:107], v[76:79], v[206:209], v[104:107]
	v_mfma_f32_16x16x32_bf16 v[92:95], v[60:63], v[214:217], v[92:95]
	v_mfma_f32_16x16x32_bf16 v[88:91], v[76:79], v[214:217], v[88:91]
	v_mfma_f32_16x16x32_bf16 v[132:135], v[162:165], v[186:189], v[132:135]
	v_mfma_f32_16x16x32_bf16 v[128:131], v[178:181], v[186:189], v[128:131]
	v_mfma_f32_16x16x32_bf16 v[116:119], v[162:165], v[194:197], v[116:119]
	v_mfma_f32_16x16x32_bf16 v[112:115], v[178:181], v[194:197], v[112:115]
	v_mfma_f32_16x16x32_bf16 v[100:103], v[162:165], v[202:205], v[100:103]
	v_mfma_f32_16x16x32_bf16 v[96:99], v[178:181], v[202:205], v[96:99]
	v_mfma_f32_16x16x32_bf16 v[84:87], v[162:165], v[210:213], v[84:87]
	v_mfma_f32_16x16x32_bf16 v[80:83], v[178:181], v[210:213], v[80:83]
	v_mfma_f32_16x16x32_bf16 v[132:135], v[166:169], v[190:193], v[132:135]
	v_mfma_f32_16x16x32_bf16 v[128:131], v[182:185], v[190:193], v[128:131]
	v_mfma_f32_16x16x32_bf16 v[116:119], v[166:169], v[198:201], v[116:119]
	v_mfma_f32_16x16x32_bf16 v[112:115], v[182:185], v[198:201], v[112:115]
	v_mfma_f32_16x16x32_bf16 v[100:103], v[166:169], v[206:209], v[100:103]
	v_mfma_f32_16x16x32_bf16 v[96:99], v[182:185], v[206:209], v[96:99]
	v_mfma_f32_16x16x32_bf16 v[84:87], v[166:169], v[214:217], v[84:87]
	v_mfma_f32_16x16x32_bf16 v[80:83], v[182:185], v[214:217], v[80:83]
	s_setprio 0
	s_barrier
	s_add_i32 s76, s64, s41
	v_lshl_add_u64 v[218:219], s[36:37], 0, v[146:147]
	s_mov_b32 m0, s76
	ds_read_b128 v[186:189], v175 offset:16384
	ds_read_b128 v[190:193], v175 offset:17408
	ds_read_b128 v[194:197], v175 offset:18432
	ds_read_b128 v[198:201], v175 offset:19456
	ds_read_b128 v[202:205], v175 offset:20480
	ds_read_b128 v[206:209], v175 offset:21504
	ds_read_b128 v[210:213], v175 offset:22528
	ds_read_b128 v[214:217], v175 offset:23552
	global_load_lds_dwordx4 v[218:219], off
	s_add_i32 m0, s76, 0x2000
	s_add_u32 s76, s36, 0x40000
	v_lshl_add_u64 v[220:221], s[36:37], 0, v[150:151]
	s_addc_u32 s77, s37, 0
	s_add_i32 s80, s65, s41
	global_load_lds_dwordx4 v[220:221], off
	v_lshl_add_u64 v[222:223], s[76:77], 0, v[146:147]
	s_mov_b32 m0, s80
	v_lshl_add_u64 v[224:225], s[38:39], 0, v[148:149]
	global_load_lds_dwordx4 v[222:223], off
	v_lshl_add_u64 v[222:223], s[76:77], 0, v[150:151]
	s_add_i32 m0, s80, 0x2000
	s_nop 0
	global_load_lds_dwordx4 v[222:223], off
	v_lshl_add_u64 v[222:223], s[38:39], 0, v[144:145]
	s_mov_b32 m0, s42
	s_nop 0
	global_load_lds_dwordx4 v[222:223], off
	s_mov_b32 m0, s43
	s_nop 0
	global_load_lds_dwordx4 v[224:225], off
	s_cmp_eq_u32 s99, 1
	s_cbranch_scc1 .Lrw_P4_1
	s_waitcnt vmcnt(8)
	s_branch .Lrj_P4_1

; #define PG8_STAGE(bufoff, gbase, voff) do { _Pragma("unroll") for (int _i = 0; _i < 2; ++_i) \
;         __builtin_amdgcn_global_load_lds((const unsigned*)((const char*)(gbase) + (voff)[_i]), (PG8_LAS unsigned*)(lds + (bufoff) + ldsw + _i * 8192), 16, 0, 0); } while (0)
; #define PG8_LDA(dst, b, h) do { _Pragma("unroll") for (int m = 0; m < 4; ++m) _Pragma("unroll") for (int k = 0; k < 2; ++k) dst[m][k] = *(const PG8_LAS bf16x8*)(lds + PG8_SA(b, h) + aoff + m * 2048 + k * 1024); } while (0)
; #define PG8_LDB(dst, b, h) do { _Pragma("unroll") for (int n = 0; n < 2; ++n) _Pragma("unroll") for (int k = 0; k < 2; ++k) dst[n][k] = *(const PG8_LAS bf16x8*)(lds + PG8_SB(b, h) + boff + n * 2048 + k * 1024); } while (0)
; #define PG8_MMA(ai, bj, At, Bt) do { __builtin_amdgcn_s_setprio(1); _Pragma("unroll") for (int m = 0; m < 4; ++m) _Pragma("unroll") for (int n = 0; n < 2; ++n) _Pragma("unroll") for (int k = 0; k < 2; ++k) \
;         acc[ai][bj][m][n] = __builtin_amdgcn_mfma_f32_16x16x32_bf16(Bt[n][k], At[m][k], acc[ai][bj][m][n], 0, 0, 0); __builtin_amdgcn_s_setprio(0); } while (0)
; #define PG8_WAIT_V(n) asm volatile("s_waitcnt vmcnt(" #n ")" ::: "memory")
; #define PG8_WAIT_L(n) asm volatile("s_waitcnt lgkmcnt(" #n ")" ::: "memory")
; #define PG8_BAR __builtin_amdgcn_s_barrier()
; #define PG8_SCHED __builtin_amdgcn_sched_barrier(0)
; template <class Epi, class Sched, bool ALIGN_EPI = false, bool SP2 = false>
; __device__ __forceinline__ void gemm_phase(PG8_LAS unsigned char* lds, const Gemm g, const Sched& S, const Epi& E) {
;     ...
;             PG8_WAIT_V(8); PG8_WAIT_L(0); PG8_BAR; PG8_MMA(1, 0, At, B0); PG8_MMA(1, 1, At, B1); PG8_BAR; PG8_SCHED;
;             PG8_LDB(B0, 1, 0); PG8_LDB(B1, 1, 1); PG8_SCHED; PG8_LDA(At, 1, 0); PG8_STAGE(PG8_SA(0, 1), a2 + hstep, voffA);
;             PG8_WAIT_V(8); PG8_WAIT_L(0); PG8_BAR; PG8_MMA(0, 0, At, B0); PG8_MMA(0, 1, At, B1); PG8_BAR; PG8_SCHED;
.Lrj_P4_1:
	s_waitcnt lgkmcnt(0)
	s_barrier
	s_setprio 1
	s_waitcnt lgkmcnt(0)
	v_mfma_f32_16x16x32_bf16 v[68:71], v[56:59], v[186:189], v[68:71]
	v_mfma_f32_16x16x32_bf16 v[64:67], v[72:75], v[186:189], v[64:67]
	v_mfma_f32_16x16x32_bf16 v[44:47], v[56:59], v[194:197], v[44:47]
	v_mfma_f32_16x16x32_bf16 v[40:43], v[72:75], v[194:197], v[40:43]
	v_mfma_f32_16x16x32_bf16 v[28:31], v[56:59], v[202:205], v[28:31]
	v_mfma_f32_16x16x32_bf16 v[24:27], v[72:75], v[202:205], v[24:27]
	v_mfma_f32_16x16x32_bf16 v[12:15], v[56:59], v[210:213], v[12:15]
	v_mfma_f32_16x16x32_bf16 v[8:11], v[72:75], v[210:213], v[8:11]
	v_mfma_f32_16x16x32_bf16 v[68:71], v[60:63], v[190:193], v[68:71]
	v_mfma_f32_16x16x32_bf16 v[64:67], v[76:79], v[190:193], v[64:67]
	v_mfma_f32_16x16x32_bf16 v[44:47], v[60:63], v[198:201], v[44:47]
	v_mfma_f32_16x16x32_bf16 v[40:43], v[76:79], v[198:201], v[40:43]
	v_mfma_f32_16x16x32_bf16 v[28:31], v[60:63], v[206:209], v[28:31]
	v_mfma_f32_16x16x32_bf16 v[24:27], v[76:79], v[206:209], v[24:27]
	v_mfma_f32_16x16x32_bf16 v[12:15], v[60:63], v[214:217], v[12:15]
	v_mfma_f32_16x16x32_bf16 v[8:11], v[76:79], v[214:217], v[8:11]
	v_mfma_f32_16x16x32_bf16 v[52:55], v[162:165], v[186:189], v[52:55]
	v_mfma_f32_16x16x32_bf16 v[48:51], v[178:181], v[186:189], v[48:51]
	v_mfma_f32_16x16x32_bf16 v[36:39], v[162:165], v[194:197], v[36:39]
	v_mfma_f32_16x16x32_bf16 v[32:35], v[178:181], v[194:197], v[32:35]
	v_mfma_f32_16x16x32_bf16 v[20:23], v[162:165], v[202:205], v[20:23]
	v_mfma_f32_16x16x32_bf16 v[16:19], v[178:181], v[202:205], v[16:19]
	v_mfma_f32_16x16x32_bf16 v[4:7], v[162:165], v[210:213], v[4:7]
	v_mfma_f32_16x16x32_bf16 v[0:3], v[178:181], v[210:213], v[0:3]
	v_mfma_f32_16x16x32_bf16 v[52:55], v[166:169], v[190:193], v[52:55]
	v_mfma_f32_16x16x32_bf16 v[48:51], v[182:185], v[190:193], v[48:51]
	v_mfma_f32_16x16x32_bf16 v[36:39], v[166:169], v[198:201], v[36:39]
	v_mfma_f32_16x16x32_bf16 v[32:35], v[182:185], v[198:201], v[32:35]
	v_mfma_f32_16x16x32_bf16 v[20:23], v[166:169], v[206:209], v[20:23]
	v_mfma_f32_16x16x32_bf16 v[16:19], v[182:185], v[206:209], v[16:19]
	v_mfma_f32_16x16x32_bf16 v[4:7], v[166:169], v[214:217], v[4:7]
	v_mfma_f32_16x16x32_bf16 v[0:3], v[182:185], v[214:217], v[0:3]
	s_setprio 0
	s_barrier
	s_add_i32 s76, 0, 0x18000
	s_add_i32 s77, 0, 0x1c000
	v_add_u32_e32 v76, s76, v171
	v_add_u32_e32 v152, s77, v171
	ds_read_b128 v[56:59], v76
	ds_read_b128 v[60:63], v76 offset:1024
	ds_read_b128 v[72:75], v76 offset:2048
	ds_read_b128 v[76:79], v76 offset:3072
	ds_read_b128 v[162:165], v152
	ds_read_b128 v[166:169], v152 offset:1024
	ds_read_b128 v[178:181], v152 offset:2048
	ds_read_b128 v[182:185], v152 offset:3072
	s_add_u32 s38, s38, 0x40000
	s_addc_u32 s39, s39, 0
	s_mov_b32 m0, s46
	v_lshl_add_u64 v[228:229], s[38:39], 0, v[144:145]
	ds_read_b128 v[186:189], v175 offset:32768
	ds_read_b128 v[190:193], v175 offset:33792
	ds_read_b128 v[194:197], v175 offset:34816
	ds_read_b128 v[198:201], v175 offset:35840
	ds_read_b128 v[202:205], v175 offset:36864
	ds_read_b128 v[206:209], v175 offset:37888
	ds_read_b128 v[210:213], v175 offset:38912
	ds_read_b128 v[214:217], v175 offset:39936
	global_load_lds_dwordx4 v[228:229], off
	v_lshl_add_u64 v[228:229], s[38:39], 0, v[148:149]
	s_mov_b32 m0, s47
	s_nop 0
	global_load_lds_dwordx4 v[228:229], off
	s_waitcnt vmcnt(8)
	s_waitcnt lgkmcnt(0)
	s_barrier
	s_setprio 1
	s_waitcnt lgkmcnt(0)
	v_mfma_f32_16x16x32_bf16 v[140:143], v[56:59], v[186:189], v[140:143]
	v_mfma_f32_16x16x32_bf16 v[136:139], v[72:75], v[186:189], v[136:139]
	v_mfma_f32_16x16x32_bf16 v[124:127], v[56:59], v[194:197], v[124:127]
	v_mfma_f32_16x16x32_bf16 v[120:123], v[72:75], v[194:197], v[120:123]
	v_mfma_f32_16x16x32_bf16 v[108:111], v[56:59], v[202:205], v[108:111]
	v_mfma_f32_16x16x32_bf16 v[104:107], v[72:75], v[202:205], v[104:107]
	v_mfma_f32_16x16x32_bf16 v[92:95], v[56:59], v[210:213], v[92:95]
	v_mfma_f32_16x16x32_bf16 v[88:91], v[72:75], v[210:213], v[88:91]
	v_mfma_f32_16x16x32_bf16 v[140:143], v[60:63], v[190:193], v[140:143]
	v_mfma_f32_16x16x32_bf16 v[136:139], v[76:79], v[190:193], v[136:139]
	v_mfma_f32_16x16x32_bf16 v[124:127], v[60:63], v[198:201], v[124:127]
	v_mfma_f32_16x16x32_bf16 v[120:123], v[76:79], v[198:201], v[120:123]
	v_mfma_f32_16x16x32_bf16 v[108:111], v[60:63], v[206:209], v[108:111]
	v_mfma_f32_16x16x32_bf16 v[104:107], v[76:79], v[206:209], v[104:107]
	v_mfma_f32_16x16x32_bf16 v[92:95], v[60:63], v[214:217], v[92:95]
	v_mfma_f32_16x16x32_bf16 v[88:91], v[76:79], v[214:217], v[88:91]
	v_mfma_f32_16x16x32_bf16 v[132:135], v[162:165], v[186:189], v[132:135]
	v_mfma_f32_16x16x32_bf16 v[128:131], v[178:181], v[186:189], v[128:131]
	v_mfma_f32_16x16x32_bf16 v[116:119], v[162:165], v[194:197], v[116:119]
	v_mfma_f32_16x16x32_bf16 v[112:115], v[178:181], v[194:197], v[112:115]
	v_mfma_f32_16x16x32_bf16 v[100:103], v[162:165], v[202:205], v[100:103]
	v_mfma_f32_16x16x32_bf16 v[96:99], v[178:181], v[202:205], v[96:99]
	v_mfma_f32_16x16x32_bf16 v[84:87], v[162:165], v[210:213], v[84:87]
	v_mfma_f32_16x16x32_bf16 v[80:83], v[178:181], v[210:213], v[80:83]
	v_mfma_f32_16x16x32_bf16 v[132:135], v[166:169], v[190:193], v[132:135]
	v_mfma_f32_16x16x32_bf16 v[128:131], v[182:185], v[190:193], v[128:131]
	v_mfma_f32_16x16x32_bf16 v[116:119], v[166:169], v[198:201], v[116:119]
	v_mfma_f32_16x16x32_bf16 v[112:115], v[182:185], v[198:201], v[112:115]
	v_mfma_f32_16x16x32_bf16 v[100:103], v[166:169], v[206:209], v[100:103]
	v_mfma_f32_16x16x32_bf16 v[96:99], v[182:185], v[206:209], v[96:99]
	v_mfma_f32_16x16x32_bf16 v[84:87], v[166:169], v[214:217], v[84:87]
	v_mfma_f32_16x16x32_bf16 v[80:83], v[182:185], v[214:217], v[80:83]
	s_setprio 0
	s_barrier
; #define PG8_STAGE(bufoff, gbase, voff) do { _Pragma("unroll") for (int _i = 0; _i < 2; ++_i) \
;         __builtin_amdgcn_global_load_lds((const unsigned*)((const char*)(gbase) + (voff)[_i]), (PG8_LAS unsigned*)(lds + (bufoff) + ldsw + _i * 8192), 16, 0, 0); } while (0)
; #define PG8_LDA(dst, b, h) do { _Pragma("unroll") for (int m = 0; m < 4; ++m) _Pragma("unroll") for (int k = 0; k < 2; ++k) dst[m][k] = *(const PG8_LAS bf16x8*)(lds + PG8_SA(b, h) + aoff + m * 2048 + k * 1024); } while (0)
; #define PG8_MMA(ai, bj, At, Bt) do { __builtin_amdgcn_s_setprio(1); _Pragma("unroll") for (int m = 0; m < 4; ++m) _Pragma("unroll") for (int n = 0; n < 2; ++n) _Pragma("unroll") for (int k = 0; k < 2; ++k) \
;         acc[ai][bj][m][n] = __builtin_amdgcn_mfma_f32_16x16x32_bf16(Bt[n][k], At[m][k], acc[ai][bj][m][n], 0, 0, 0); __builtin_amdgcn_s_setprio(0); } while (0)
; #define PG8_WAIT_V(n) asm volatile("s_waitcnt vmcnt(" #n ")" ::: "memory")
; #define PG8_WAIT_L(n) asm volatile("s_waitcnt lgkmcnt(" #n ")" ::: "memory")
; #define PG8_BAR __builtin_amdgcn_s_barrier()
; #define PG8_SCHED __builtin_amdgcn_sched_barrier(0)
; template <class Epi, class Sched, bool ALIGN_EPI = false, bool SP2 = false>
; __device__ __forceinline__ void gemm_phase(PG8_LAS unsigned char* lds, const Gemm g, const Sched& S, const Epi& E) {
;     ...
;             PG8_LDA(At, 1, 1); PG8_STAGE(PG8_SB(1, 0), b3, voffB); PG8_STAGE(PG8_SB(1, 1), b3 + hstep, voffB); PG8_STAGE(PG8_SA(1, 0), a3, voffA);
;             PG8_WAIT_V(8); PG8_WAIT_L(0); PG8_BAR; PG8_MMA(1, 0, At, B0); PG8_MMA(1, 1, At, B1); PG8_BAR; PG8_SCHED;
;     ...
;         if constexpr (ALIGN_EPI) { if (wr == 0) PG8_BAR; }
	s_add_i32 s38, s76, s41
	v_lshl_add_u64 v[218:219], v[218:219], 0, s[18:19]
	s_mov_b32 m0, s38
	ds_read_b128 v[186:189], v175 offset:49152
	ds_read_b128 v[190:193], v175 offset:50176
	ds_read_b128 v[194:197], v175 offset:51200
	ds_read_b128 v[198:201], v175 offset:52224
	ds_read_b128 v[202:205], v175 offset:53248
	ds_read_b128 v[206:209], v175 offset:54272
	ds_read_b128 v[210:213], v175 offset:55296
	ds_read_b128 v[214:217], v175 offset:56320
	global_load_lds_dwordx4 v[218:219], off
	s_add_i32 m0, s38, 0x2000
	s_add_u32 s36, s36, 0x40080
	v_lshl_add_u64 v[218:219], v[220:221], 0, s[18:19]
	s_addc_u32 s37, s37, 0
	s_add_i32 s38, s77, s41
	global_load_lds_dwordx4 v[218:219], off
	v_lshl_add_u64 v[218:219], s[36:37], 0, v[146:147]
	s_mov_b32 m0, s38
	s_nop 0
	global_load_lds_dwordx4 v[218:219], off
	v_lshl_add_u64 v[218:219], s[36:37], 0, v[150:151]
	s_add_i32 m0, s38, 0x2000
	s_nop 0
	global_load_lds_dwordx4 v[218:219], off
	v_lshl_add_u64 v[218:219], v[222:223], 0, s[18:19]
	s_mov_b32 m0, s53
	s_nop 0
	global_load_lds_dwordx4 v[218:219], off
	v_lshl_add_u64 v[218:219], v[224:225], 0, s[18:19]
	s_mov_b32 m0, s60
	s_nop 0
	global_load_lds_dwordx4 v[218:219], off
	s_waitcnt vmcnt(8)
	s_waitcnt lgkmcnt(0)
	s_barrier
	s_setprio 1
	s_waitcnt lgkmcnt(0)
	v_mfma_f32_16x16x32_bf16 v[68:71], v[56:59], v[186:189], v[68:71]
	v_mfma_f32_16x16x32_bf16 v[64:67], v[72:75], v[186:189], v[64:67]
	v_mfma_f32_16x16x32_bf16 v[44:47], v[56:59], v[194:197], v[44:47]
	v_mfma_f32_16x16x32_bf16 v[40:43], v[72:75], v[194:197], v[40:43]
	v_mfma_f32_16x16x32_bf16 v[28:31], v[56:59], v[202:205], v[28:31]
	v_mfma_f32_16x16x32_bf16 v[24:27], v[72:75], v[202:205], v[24:27]
	v_mfma_f32_16x16x32_bf16 v[12:15], v[56:59], v[210:213], v[12:15]
	v_mfma_f32_16x16x32_bf16 v[8:11], v[72:75], v[210:213], v[8:11]
	v_mfma_f32_16x16x32_bf16 v[68:71], v[60:63], v[190:193], v[68:71]
	v_mfma_f32_16x16x32_bf16 v[64:67], v[76:79], v[190:193], v[64:67]
	v_mfma_f32_16x16x32_bf16 v[44:47], v[60:63], v[198:201], v[44:47]
	v_mfma_f32_16x16x32_bf16 v[40:43], v[76:79], v[198:201], v[40:43]
	v_mfma_f32_16x16x32_bf16 v[28:31], v[60:63], v[206:209], v[28:31]
	v_mfma_f32_16x16x32_bf16 v[24:27], v[76:79], v[206:209], v[24:27]
	v_mfma_f32_16x16x32_bf16 v[12:15], v[60:63], v[214:217], v[12:15]
	v_mfma_f32_16x16x32_bf16 v[8:11], v[76:79], v[214:217], v[8:11]
	v_mfma_f32_16x16x32_bf16 v[52:55], v[162:165], v[186:189], v[52:55]
	v_mfma_f32_16x16x32_bf16 v[48:51], v[178:181], v[186:189], v[48:51]
	v_mfma_f32_16x16x32_bf16 v[36:39], v[162:165], v[194:197], v[36:39]
	v_mfma_f32_16x16x32_bf16 v[32:35], v[178:181], v[194:197], v[32:35]
	v_mfma_f32_16x16x32_bf16 v[20:23], v[162:165], v[202:205], v[20:23]
	v_mfma_f32_16x16x32_bf16 v[16:19], v[178:181], v[202:205], v[16:19]
	v_mfma_f32_16x16x32_bf16 v[4:7], v[162:165], v[210:213], v[4:7]
	v_mfma_f32_16x16x32_bf16 v[0:3], v[178:181], v[210:213], v[0:3]
	v_mfma_f32_16x16x32_bf16 v[52:55], v[166:169], v[190:193], v[52:55]
	v_mfma_f32_16x16x32_bf16 v[48:51], v[182:185], v[190:193], v[48:51]
	v_mfma_f32_16x16x32_bf16 v[36:39], v[166:169], v[198:201], v[36:39]
	v_mfma_f32_16x16x32_bf16 v[32:35], v[182:185], v[198:201], v[32:35]
	v_mfma_f32_16x16x32_bf16 v[20:23], v[166:169], v[206:209], v[20:23]
	v_mfma_f32_16x16x32_bf16 v[16:19], v[182:185], v[206:209], v[16:19]
	v_mfma_f32_16x16x32_bf16 v[4:7], v[166:169], v[214:217], v[4:7]
	v_mfma_f32_16x16x32_bf16 v[0:3], v[182:185], v[214:217], v[0:3]
	s_setprio 0
	s_barrier
	s_mov_b32 s99, 0
	s_add_i32 s75, s75, 2
	s_add_u32 s34, s34, 0x100
	s_addc_u32 s35, s35, 0
	s_add_u32 s73, s73, 0x100
	s_addc_u32 s74, s74, 0
	s_cmp_gt_u32 s75, 13
	s_cbranch_scc0 .LBB0_1423
	s_and_b64 vcc, exec, s[20:21]
	s_cbranch_vccz .LBB0_1426
	s_barrier

; #define PG8_STAGE(bufoff, gbase, voff) do { _Pragma("unroll") for (int _i = 0; _i < 2; ++_i) \
;         __builtin_amdgcn_global_load_lds((const unsigned*)((const char*)(gbase) + (voff)[_i]), (PG8_LAS unsigned*)(lds + (bufoff) + ldsw + _i * 8192), 16, 0, 0); } while (0)
; #define PG8_LDA(dst, b, h) do { _Pragma("unroll") for (int m = 0; m < 4; ++m) _Pragma("unroll") for (int k = 0; k < 2; ++k) dst[m][k] = *(const PG8_LAS bf16x8*)(lds + PG8_SA(b, h) + aoff + m * 2048 + k * 1024); } while (0)
; #define PG8_MMA(ai, bj, At, Bt) do { __builtin_amdgcn_s_setprio(1); _Pragma("unroll") for (int m = 0; m < 4; ++m) _Pragma("unroll") for (int n = 0; n < 2; ++n) _Pragma("unroll") for (int k = 0; k < 2; ++k) \
;         acc[ai][bj][m][n] = __builtin_amdgcn_mfma_f32_16x16x32_bf16(Bt[n][k], At[m][k], acc[ai][bj][m][n], 0, 0, 0); __builtin_amdgcn_s_setprio(0); } while (0)
; #define PG8_WAIT_V(n) asm volatile("s_waitcnt vmcnt(" #n ")" ::: "memory")
; #define PG8_WAIT_L(n) asm volatile("s_waitcnt lgkmcnt(" #n ")" ::: "memory")
; #define PG8_BAR __builtin_amdgcn_s_barrier()
; #define PG8_SCHED __builtin_amdgcn_sched_barrier(0)
; template <class Epi, class Sched, bool ALIGN_EPI = false, bool SP2 = false>
; __device__ __forceinline__ void gemm_phase(PG8_LAS unsigned char* lds, const Gemm g, const Sched& S, const Epi& E) {
;     ...
;             PG8_WAIT_V(8); PG8_WAIT_L(0); PG8_BAR; PG8_MMA(0, 0, At, B0); PG8_MMA(0, 1, At, B1); PG8_BAR; PG8_SCHED;
;             PG8_LDA(At, 0, 1); PG8_STAGE(PG8_SB(0, 0), b2, voffB); PG8_STAGE(PG8_SB(0, 1), b2 + hstep, voffB); PG8_STAGE(PG8_SA(0, 0), a2, voffA);
.Lrj_P5_0:
	s_waitcnt lgkmcnt(0)
	s_barrier
	s_setprio 1
	s_waitcnt lgkmcnt(0)
	v_mfma_f32_16x16x32_bf16 v[124:127], v[144:147], v[184:187], v[124:127]
	v_mfma_f32_16x16x32_bf16 v[120:123], v[160:163], v[184:187], v[120:123]
	v_mfma_f32_16x16x32_bf16 v[108:111], v[144:147], v[192:195], v[108:111]
	v_mfma_f32_16x16x32_bf16 v[104:107], v[160:163], v[192:195], v[104:107]
	v_mfma_f32_16x16x32_bf16 v[92:95], v[144:147], v[200:203], v[92:95]
	v_mfma_f32_16x16x32_bf16 v[88:91], v[160:163], v[200:203], v[88:91]
	v_mfma_f32_16x16x32_bf16 v[76:79], v[144:147], v[208:211], v[76:79]
	v_mfma_f32_16x16x32_bf16 v[72:75], v[160:163], v[208:211], v[72:75]
	v_mfma_f32_16x16x32_bf16 v[124:127], v[156:159], v[188:191], v[124:127]
	v_mfma_f32_16x16x32_bf16 v[120:123], v[164:167], v[188:191], v[120:123]
	v_mfma_f32_16x16x32_bf16 v[108:111], v[156:159], v[196:199], v[108:111]
	v_mfma_f32_16x16x32_bf16 v[104:107], v[164:167], v[196:199], v[104:107]
	v_mfma_f32_16x16x32_bf16 v[92:95], v[156:159], v[204:207], v[92:95]
	v_mfma_f32_16x16x32_bf16 v[88:91], v[164:167], v[204:207], v[88:91]
	v_mfma_f32_16x16x32_bf16 v[76:79], v[156:159], v[212:215], v[76:79]
	v_mfma_f32_16x16x32_bf16 v[72:75], v[164:167], v[212:215], v[72:75]
	v_mfma_f32_16x16x32_bf16 v[116:119], v[168:171], v[184:187], v[116:119]
	v_mfma_f32_16x16x32_bf16 v[112:115], v[176:179], v[184:187], v[112:115]
	v_mfma_f32_16x16x32_bf16 v[100:103], v[168:171], v[192:195], v[100:103]
	v_mfma_f32_16x16x32_bf16 v[96:99], v[176:179], v[192:195], v[96:99]
	v_mfma_f32_16x16x32_bf16 v[84:87], v[168:171], v[200:203], v[84:87]
	v_mfma_f32_16x16x32_bf16 v[80:83], v[176:179], v[200:203], v[80:83]
	v_mfma_f32_16x16x32_bf16 v[68:71], v[168:171], v[208:211], v[68:71]
	v_mfma_f32_16x16x32_bf16 v[64:67], v[176:179], v[208:211], v[64:67]
	v_mfma_f32_16x16x32_bf16 v[116:119], v[172:175], v[188:191], v[116:119]
	v_mfma_f32_16x16x32_bf16 v[112:115], v[180:183], v[188:191], v[112:115]
	v_mfma_f32_16x16x32_bf16 v[100:103], v[172:175], v[196:199], v[100:103]
	v_mfma_f32_16x16x32_bf16 v[96:99], v[180:183], v[196:199], v[96:99]
	v_mfma_f32_16x16x32_bf16 v[84:87], v[172:175], v[204:207], v[84:87]
	v_mfma_f32_16x16x32_bf16 v[80:83], v[180:183], v[204:207], v[80:83]
	v_mfma_f32_16x16x32_bf16 v[68:71], v[172:175], v[212:215], v[68:71]
	v_mfma_f32_16x16x32_bf16 v[64:67], v[180:183], v[212:215], v[64:67]
	s_setprio 0
	s_barrier
	s_add_i32 s66, s52, s39
	v_lshl_add_u64 v[216:217], s[34:35], 0, v[132:133]
	s_mov_b32 m0, s66
	ds_read_b128 v[184:187], v153 offset:16384
	ds_read_b128 v[188:191], v153 offset:17408
	ds_read_b128 v[192:195], v153 offset:18432
	ds_read_b128 v[196:199], v153 offset:19456
	ds_read_b128 v[200:203], v153 offset:20480
	ds_read_b128 v[204:207], v153 offset:21504
	ds_read_b128 v[208:211], v153 offset:22528
	ds_read_b128 v[212:215], v153 offset:23552
	global_load_lds_dwordx4 v[216:217], off
	s_add_i32 m0, s66, 0x2000
	s_add_u32 s66, s34, 0x40000
	v_lshl_add_u64 v[218:219], s[34:35], 0, v[128:129]
	s_addc_u32 s67, s35, 0
	s_add_i32 s68, s53, s39
	global_load_lds_dwordx4 v[218:219], off
	v_lshl_add_u64 v[220:221], s[66:67], 0, v[132:133]
	s_mov_b32 m0, s68
	v_lshl_add_u64 v[222:223], s[36:37], 0, v[130:131]
	global_load_lds_dwordx4 v[220:221], off
	v_lshl_add_u64 v[220:221], s[66:67], 0, v[128:129]
	s_add_i32 m0, s68, 0x2000
	s_nop 0
	global_load_lds_dwordx4 v[220:221], off
	v_lshl_add_u64 v[220:221], s[36:37], 0, v[134:135]
	s_mov_b32 m0, s29
	s_nop 0
	global_load_lds_dwordx4 v[220:221], off
	s_mov_b32 m0, s42
	s_nop 0
	global_load_lds_dwordx4 v[222:223], off
	s_cmp_eq_u32 s99, 1
	s_cbranch_scc1 .Lrw_P5_1
	s_waitcnt vmcnt(8)
	s_branch .Lrj_P5_1

; #define PG8_STAGE(bufoff, gbase, voff) do { _Pragma("unroll") for (int _i = 0; _i < 2; ++_i) \
;         __builtin_amdgcn_global_load_lds((const unsigned*)((const char*)(gbase) + (voff)[_i]), (PG8_LAS unsigned*)(lds + (bufoff) + ldsw + _i * 8192), 16, 0, 0); } while (0)
; #define PG8_LDA(dst, b, h) do { _Pragma("unroll") for (int m = 0; m < 4; ++m) _Pragma("unroll") for (int k = 0; k < 2; ++k) dst[m][k] = *(const PG8_LAS bf16x8*)(lds + PG8_SA(b, h) + aoff + m * 2048 + k * 1024); } while (0)
; #define PG8_LDB(dst, b, h) do { _Pragma("unroll") for (int n = 0; n < 2; ++n) _Pragma("unroll") for (int k = 0; k < 2; ++k) dst[n][k] = *(const PG8_LAS bf16x8*)(lds + PG8_SB(b, h) + boff + n * 2048 + k * 1024); } while (0)
; #define PG8_MMA(ai, bj, At, Bt) do { __builtin_amdgcn_s_setprio(1); _Pragma("unroll") for (int m = 0; m < 4; ++m) _Pragma("unroll") for (int n = 0; n < 2; ++n) _Pragma("unroll") for (int k = 0; k < 2; ++k) \
;         acc[ai][bj][m][n] = __builtin_amdgcn_mfma_f32_16x16x32_bf16(Bt[n][k], At[m][k], acc[ai][bj][m][n], 0, 0, 0); __builtin_amdgcn_s_setprio(0); } while (0)
; #define PG8_WAIT_V(n) asm volatile("s_waitcnt vmcnt(" #n ")" ::: "memory")
; #define PG8_WAIT_L(n) asm volatile("s_waitcnt lgkmcnt(" #n ")" ::: "memory")
; #define PG8_BAR __builtin_amdgcn_s_barrier()
; #define PG8_SCHED __builtin_amdgcn_sched_barrier(0)
; template <class Epi, class Sched, bool ALIGN_EPI = false, bool SP2 = false>
; __device__ __forceinline__ void gemm_phase(PG8_LAS unsigned char* lds, const Gemm g, const Sched& S, const Epi& E) {
;     ...
;             PG8_WAIT_V(8); PG8_WAIT_L(0); PG8_BAR; PG8_MMA(1, 0, At, B0); PG8_MMA(1, 1, At, B1); PG8_BAR; PG8_SCHED;
;             PG8_LDB(B0, 1, 0); PG8_LDB(B1, 1, 1); PG8_SCHED; PG8_LDA(At, 1, 0); PG8_STAGE(PG8_SA(0, 1), a2 + hstep, voffA);
;             PG8_WAIT_V(8); PG8_WAIT_L(0); PG8_BAR; PG8_MMA(0, 0, At, B0); PG8_MMA(0, 1, At, B1); PG8_BAR; PG8_SCHED;
.Lrj_P5_1:
	s_waitcnt lgkmcnt(0)
	s_barrier
	s_setprio 1
	s_waitcnt lgkmcnt(0)
	v_mfma_f32_16x16x32_bf16 v[60:63], v[144:147], v[184:187], v[60:63]
	v_mfma_f32_16x16x32_bf16 v[56:59], v[160:163], v[184:187], v[56:59]
	v_mfma_f32_16x16x32_bf16 v[44:47], v[144:147], v[192:195], v[44:47]
	v_mfma_f32_16x16x32_bf16 v[40:43], v[160:163], v[192:195], v[40:43]
	v_mfma_f32_16x16x32_bf16 v[28:31], v[144:147], v[200:203], v[28:31]
	v_mfma_f32_16x16x32_bf16 v[24:27], v[160:163], v[200:203], v[24:27]
	v_mfma_f32_16x16x32_bf16 v[12:15], v[144:147], v[208:211], v[12:15]
	v_mfma_f32_16x16x32_bf16 v[8:11], v[160:163], v[208:211], v[8:11]
	v_mfma_f32_16x16x32_bf16 v[60:63], v[156:159], v[188:191], v[60:63]
	v_mfma_f32_16x16x32_bf16 v[56:59], v[164:167], v[188:191], v[56:59]
	v_mfma_f32_16x16x32_bf16 v[44:47], v[156:159], v[196:199], v[44:47]
	v_mfma_f32_16x16x32_bf16 v[40:43], v[164:167], v[196:199], v[40:43]
	v_mfma_f32_16x16x32_bf16 v[28:31], v[156:159], v[204:207], v[28:31]
	v_mfma_f32_16x16x32_bf16 v[24:27], v[164:167], v[204:207], v[24:27]
	v_mfma_f32_16x16x32_bf16 v[12:15], v[156:159], v[212:215], v[12:15]
	v_mfma_f32_16x16x32_bf16 v[8:11], v[164:167], v[212:215], v[8:11]
	v_mfma_f32_16x16x32_bf16 v[52:55], v[168:171], v[184:187], v[52:55]
	v_mfma_f32_16x16x32_bf16 v[48:51], v[176:179], v[184:187], v[48:51]
	v_mfma_f32_16x16x32_bf16 v[36:39], v[168:171], v[192:195], v[36:39]
	v_mfma_f32_16x16x32_bf16 v[32:35], v[176:179], v[192:195], v[32:35]
	v_mfma_f32_16x16x32_bf16 v[20:23], v[168:171], v[200:203], v[20:23]
	v_mfma_f32_16x16x32_bf16 v[16:19], v[176:179], v[200:203], v[16:19]
	v_mfma_f32_16x16x32_bf16 v[4:7], v[168:171], v[208:211], v[4:7]
	v_mfma_f32_16x16x32_bf16 v[0:3], v[176:179], v[208:211], v[0:3]
	v_mfma_f32_16x16x32_bf16 v[52:55], v[172:175], v[188:191], v[52:55]
	v_mfma_f32_16x16x32_bf16 v[48:51], v[180:183], v[188:191], v[48:51]
	v_mfma_f32_16x16x32_bf16 v[36:39], v[172:175], v[196:199], v[36:39]
	v_mfma_f32_16x16x32_bf16 v[32:35], v[180:183], v[196:199], v[32:35]
	v_mfma_f32_16x16x32_bf16 v[20:23], v[172:175], v[204:207], v[20:23]
	v_mfma_f32_16x16x32_bf16 v[16:19], v[180:183], v[204:207], v[16:19]
	v_mfma_f32_16x16x32_bf16 v[4:7], v[172:175], v[212:215], v[4:7]
	v_mfma_f32_16x16x32_bf16 v[0:3], v[180:183], v[212:215], v[0:3]
	s_setprio 0
	s_barrier
	s_add_i32 s66, 0, 0x18000
	v_add_u32_e32 v155, s66, v149
	s_add_i32 s67, 0, 0x1c000
	ds_read_b128 v[144:147], v155
	ds_read_b128 v[156:159], v155 offset:1024
	ds_read_b128 v[160:163], v155 offset:2048
	ds_read_b128 v[164:167], v155 offset:3072
	v_add_u32_e32 v155, s67, v149
	ds_read_b128 v[168:171], v155
	ds_read_b128 v[172:175], v155 offset:1024
	ds_read_b128 v[176:179], v155 offset:2048
	ds_read_b128 v[180:183], v155 offset:3072
	s_add_u32 s36, s36, 0x40000
	s_addc_u32 s37, s37, 0
	s_mov_b32 m0, s43
	v_lshl_add_u64 v[224:225], s[36:37], 0, v[134:135]
	ds_read_b128 v[184:187], v153 offset:32768
	ds_read_b128 v[188:191], v153 offset:33792
	ds_read_b128 v[192:195], v153 offset:34816
	ds_read_b128 v[196:199], v153 offset:35840
	ds_read_b128 v[200:203], v153 offset:36864
	ds_read_b128 v[204:207], v153 offset:37888
	ds_read_b128 v[208:211], v153 offset:38912
	ds_read_b128 v[212:215], v153 offset:39936
	global_load_lds_dwordx4 v[224:225], off
	v_lshl_add_u64 v[224:225], s[36:37], 0, v[130:131]
	s_mov_b32 m0, s46
	s_nop 0
	global_load_lds_dwordx4 v[224:225], off
	s_waitcnt vmcnt(8)
	s_waitcnt lgkmcnt(0)
	s_barrier
	s_setprio 1
	s_waitcnt lgkmcnt(0)
	v_mfma_f32_16x16x32_bf16 v[124:127], v[144:147], v[184:187], v[124:127]
	v_mfma_f32_16x16x32_bf16 v[120:123], v[160:163], v[184:187], v[120:123]
	v_mfma_f32_16x16x32_bf16 v[108:111], v[144:147], v[192:195], v[108:111]
	v_mfma_f32_16x16x32_bf16 v[104:107], v[160:163], v[192:195], v[104:107]
	v_mfma_f32_16x16x32_bf16 v[92:95], v[144:147], v[200:203], v[92:95]
	v_mfma_f32_16x16x32_bf16 v[88:91], v[160:163], v[200:203], v[88:91]
	v_mfma_f32_16x16x32_bf16 v[76:79], v[144:147], v[208:211], v[76:79]
	v_mfma_f32_16x16x32_bf16 v[72:75], v[160:163], v[208:211], v[72:75]
	v_mfma_f32_16x16x32_bf16 v[124:127], v[156:159], v[188:191], v[124:127]
	v_mfma_f32_16x16x32_bf16 v[120:123], v[164:167], v[188:191], v[120:123]
	v_mfma_f32_16x16x32_bf16 v[108:111], v[156:159], v[196:199], v[108:111]
	v_mfma_f32_16x16x32_bf16 v[104:107], v[164:167], v[196:199], v[104:107]
	v_mfma_f32_16x16x32_bf16 v[92:95], v[156:159], v[204:207], v[92:95]
	v_mfma_f32_16x16x32_bf16 v[88:91], v[164:167], v[204:207], v[88:91]
	v_mfma_f32_16x16x32_bf16 v[76:79], v[156:159], v[212:215], v[76:79]
	v_mfma_f32_16x16x32_bf16 v[72:75], v[164:167], v[212:215], v[72:75]
	v_mfma_f32_16x16x32_bf16 v[116:119], v[168:171], v[184:187], v[116:119]
	v_mfma_f32_16x16x32_bf16 v[112:115], v[176:179], v[184:187], v[112:115]
	v_mfma_f32_16x16x32_bf16 v[100:103], v[168:171], v[192:195], v[100:103]
	v_mfma_f32_16x16x32_bf16 v[96:99], v[176:179], v[192:195], v[96:99]
	v_mfma_f32_16x16x32_bf16 v[84:87], v[168:171], v[200:203], v[84:87]
	v_mfma_f32_16x16x32_bf16 v[80:83], v[176:179], v[200:203], v[80:83]
	v_mfma_f32_16x16x32_bf16 v[68:71], v[168:171], v[208:211], v[68:71]
	v_mfma_f32_16x16x32_bf16 v[64:67], v[176:179], v[208:211], v[64:67]
	v_mfma_f32_16x16x32_bf16 v[116:119], v[172:175], v[188:191], v[116:119]
	v_mfma_f32_16x16x32_bf16 v[112:115], v[180:183], v[188:191], v[112:115]
	v_mfma_f32_16x16x32_bf16 v[100:103], v[172:175], v[196:199], v[100:103]
	v_mfma_f32_16x16x32_bf16 v[96:99], v[180:183], v[196:199], v[96:99]
	v_mfma_f32_16x16x32_bf16 v[84:87], v[172:175], v[204:207], v[84:87]
	v_mfma_f32_16x16x32_bf16 v[80:83], v[180:183], v[204:207], v[80:83]
	v_mfma_f32_16x16x32_bf16 v[68:71], v[172:175], v[212:215], v[68:71]
	v_mfma_f32_16x16x32_bf16 v[64:67], v[180:183], v[212:215], v[64:67]
	s_setprio 0
	s_barrier
; #define PG8_STAGE(bufoff, gbase, voff) do { _Pragma("unroll") for (int _i = 0; _i < 2; ++_i) \
;         __builtin_amdgcn_global_load_lds((const unsigned*)((const char*)(gbase) + (voff)[_i]), (PG8_LAS unsigned*)(lds + (bufoff) + ldsw + _i * 8192), 16, 0, 0); } while (0)
; #define PG8_LDA(dst, b, h) do { _Pragma("unroll") for (int m = 0; m < 4; ++m) _Pragma("unroll") for (int k = 0; k < 2; ++k) dst[m][k] = *(const PG8_LAS bf16x8*)(lds + PG8_SA(b, h) + aoff + m * 2048 + k * 1024); } while (0)
; #define PG8_MMA(ai, bj, At, Bt) do { __builtin_amdgcn_s_setprio(1); _Pragma("unroll") for (int m = 0; m < 4; ++m) _Pragma("unroll") for (int n = 0; n < 2; ++n) _Pragma("unroll") for (int k = 0; k < 2; ++k) \
;         acc[ai][bj][m][n] = __builtin_amdgcn_mfma_f32_16x16x32_bf16(Bt[n][k], At[m][k], acc[ai][bj][m][n], 0, 0, 0); __builtin_amdgcn_s_setprio(0); } while (0)
; #define PG8_WAIT_V(n) asm volatile("s_waitcnt vmcnt(" #n ")" ::: "memory")
; #define PG8_WAIT_L(n) asm volatile("s_waitcnt lgkmcnt(" #n ")" ::: "memory")
; #define PG8_BAR __builtin_amdgcn_s_barrier()
; #define PG8_SCHED __builtin_amdgcn_sched_barrier(0)
; template <class Epi, class Sched, bool ALIGN_EPI = false, bool SP2 = false>
; __device__ __forceinline__ void gemm_phase(PG8_LAS unsigned char* lds, const Gemm g, const Sched& S, const Epi& E) {
;     ...
;             PG8_LDA(At, 1, 1); PG8_STAGE(PG8_SB(1, 0), b3, voffB); PG8_STAGE(PG8_SB(1, 1), b3 + hstep, voffB); PG8_STAGE(PG8_SA(1, 0), a3, voffA);
;             PG8_WAIT_V(8); PG8_WAIT_L(0); PG8_BAR; PG8_MMA(1, 0, At, B0); PG8_MMA(1, 1, At, B1); PG8_BAR; PG8_SCHED;
;     __device__ __forceinline__ void operator()(const f32x4 (&acc)[2][2][4][2], const Unit& u, int wr, int wc, int fr, int fq) const {
;     ...
;             for (int m = 0; m < 4; ++m) { const int row = rbase + ai * 128 + m * 16; const f32x4* sp = (const f32x4*)(SSP + (size_t)row * 16);
;                 const f32x4 s4 = (sp[0] + sp[1]) + (sp[2] + sp[3]); const float rstd = __builtin_amdgcn_rsqf(((s4[0] + s4[1]) + (s4[2] + s4[3])) * (1.0f / 1024.0f) + EPS);
	s_add_i32 s36, s66, s39
	v_lshl_add_u64 v[216:217], v[216:217], 0, s[14:15]
	s_mov_b32 m0, s36
	ds_read_b128 v[184:187], v153 offset:49152
	ds_read_b128 v[188:191], v153 offset:50176
	ds_read_b128 v[192:195], v153 offset:51200
	ds_read_b128 v[196:199], v153 offset:52224
	ds_read_b128 v[200:203], v153 offset:53248
	ds_read_b128 v[204:207], v153 offset:54272
	ds_read_b128 v[208:211], v153 offset:55296
	ds_read_b128 v[212:215], v153 offset:56320
	global_load_lds_dwordx4 v[216:217], off
	s_add_i32 m0, s36, 0x2000
	s_add_u32 s34, s34, 0x40080
	v_lshl_add_u64 v[216:217], v[218:219], 0, s[14:15]
	s_addc_u32 s35, s35, 0
	s_add_i32 s36, s67, s39
	global_load_lds_dwordx4 v[216:217], off
	v_lshl_add_u64 v[216:217], s[34:35], 0, v[132:133]
	s_mov_b32 m0, s36
	s_nop 0
	global_load_lds_dwordx4 v[216:217], off
	v_lshl_add_u64 v[216:217], s[34:35], 0, v[128:129]
	s_add_i32 m0, s36, 0x2000
	s_nop 0
	global_load_lds_dwordx4 v[216:217], off
	v_lshl_add_u64 v[216:217], v[220:221], 0, s[14:15]
	s_mov_b32 m0, s49
	s_nop 0
	global_load_lds_dwordx4 v[216:217], off
	v_lshl_add_u64 v[216:217], v[222:223], 0, s[14:15]
	s_mov_b32 m0, s50
	s_nop 0
	global_load_lds_dwordx4 v[216:217], off
	s_waitcnt vmcnt(8)
	s_waitcnt lgkmcnt(0)
	s_barrier
	s_setprio 1
	s_waitcnt lgkmcnt(0)
	v_mfma_f32_16x16x32_bf16 v[60:63], v[144:147], v[184:187], v[60:63]
	v_mfma_f32_16x16x32_bf16 v[56:59], v[160:163], v[184:187], v[56:59]
	v_mfma_f32_16x16x32_bf16 v[44:47], v[144:147], v[192:195], v[44:47]
	v_mfma_f32_16x16x32_bf16 v[40:43], v[160:163], v[192:195], v[40:43]
	v_mfma_f32_16x16x32_bf16 v[28:31], v[144:147], v[200:203], v[28:31]
	v_mfma_f32_16x16x32_bf16 v[24:27], v[160:163], v[200:203], v[24:27]
	v_mfma_f32_16x16x32_bf16 v[12:15], v[144:147], v[208:211], v[12:15]
	v_mfma_f32_16x16x32_bf16 v[8:11], v[160:163], v[208:211], v[8:11]
	v_mfma_f32_16x16x32_bf16 v[60:63], v[156:159], v[188:191], v[60:63]
	v_mfma_f32_16x16x32_bf16 v[56:59], v[164:167], v[188:191], v[56:59]
	v_mfma_f32_16x16x32_bf16 v[44:47], v[156:159], v[196:199], v[44:47]
	v_mfma_f32_16x16x32_bf16 v[40:43], v[164:167], v[196:199], v[40:43]
	v_mfma_f32_16x16x32_bf16 v[28:31], v[156:159], v[204:207], v[28:31]
	v_mfma_f32_16x16x32_bf16 v[24:27], v[164:167], v[204:207], v[24:27]
	v_mfma_f32_16x16x32_bf16 v[12:15], v[156:159], v[212:215], v[12:15]
	v_mfma_f32_16x16x32_bf16 v[8:11], v[164:167], v[212:215], v[8:11]
	v_mfma_f32_16x16x32_bf16 v[52:55], v[168:171], v[184:187], v[52:55]
	v_mfma_f32_16x16x32_bf16 v[48:51], v[176:179], v[184:187], v[48:51]
	v_mfma_f32_16x16x32_bf16 v[36:39], v[168:171], v[192:195], v[36:39]
	v_mfma_f32_16x16x32_bf16 v[32:35], v[176:179], v[192:195], v[32:35]
	v_mfma_f32_16x16x32_bf16 v[20:23], v[168:171], v[200:203], v[20:23]
	v_mfma_f32_16x16x32_bf16 v[16:19], v[176:179], v[200:203], v[16:19]
	v_mfma_f32_16x16x32_bf16 v[4:7], v[168:171], v[208:211], v[4:7]
	v_mfma_f32_16x16x32_bf16 v[0:3], v[176:179], v[208:211], v[0:3]
	v_mfma_f32_16x16x32_bf16 v[52:55], v[172:175], v[188:191], v[52:55]
	v_mfma_f32_16x16x32_bf16 v[48:51], v[180:183], v[188:191], v[48:51]
	v_mfma_f32_16x16x32_bf16 v[36:39], v[172:175], v[196:199], v[36:39]
	v_mfma_f32_16x16x32_bf16 v[32:35], v[180:183], v[196:199], v[32:35]
	v_mfma_f32_16x16x32_bf16 v[20:23], v[172:175], v[204:207], v[20:23]
	v_mfma_f32_16x16x32_bf16 v[16:19], v[180:183], v[204:207], v[16:19]
	v_mfma_f32_16x16x32_bf16 v[4:7], v[172:175], v[212:215], v[4:7]
	v_mfma_f32_16x16x32_bf16 v[0:3], v[180:183], v[212:215], v[0:3]
	s_setprio 0
	s_barrier
	s_mov_b32 s99, 0
	s_add_i32 s65, s65, 2
	s_add_u32 s30, s30, 0x100
	s_addc_u32 s31, s31, 0
	s_add_u32 s63, s63, 0x100
	s_addc_u32 s64, s64, 0
	s_cmp_gt_u32 s65, 13
	s_cbranch_scc0 .LBB0_1540
	v_lshl_add_u32 v146, s28, 8, v148
	v_ashrrev_i32_e32 v147, 31, v146
	v_lshlrev_b64 v[144:145], 6, v[146:147]
	v_lshl_add_u64 v[144:145], s[12:13], 0, v[144:145]
	global_load_dwordx4 v[156:159], v[144:145], off
	global_load_dwordx4 v[160:163], v[144:145], off offset:16
	global_load_dwordx4 v[164:167], v[144:145], off offset:32
	global_load_dwordx4 v[168:171], v[144:145], off offset:48
	global_load_dwordx4 v[172:175], v[144:145], off offset:1024
	global_load_dwordx4 v[176:179], v[144:145], off offset:1040
	global_load_dwordx4 v[180:183], v[144:145], off offset:1056
	global_load_dwordx4 v[184:187], v[144:145], off offset:1072
	global_load_dwordx4 v[188:191], v[144:145], off offset:2048
	global_load_dwordx4 v[192:195], v[144:145], off offset:2064
	global_load_dwordx4 v[196:199], v[144:145], off offset:2080
	global_load_dwordx4 v[200:203], v[144:145], off offset:2096
	global_load_dwordx4 v[204:207], v[144:145], off offset:3072
	global_load_dwordx4 v[208:211], v[144:145], off offset:3088
	global_load_dwordx4 v[212:215], v[144:145], off offset:3104
	global_load_dwordx4 v[216:219], v[144:145], off offset:3120
	s_and_b64 vcc, exec, s[16:17]
	s_cbranch_vccz .LBB0_1543
	s_barrier

; #define PG8_STAGE(bufoff, gbase, voff) do { _Pragma("unroll") for (int _i = 0; _i < 2; ++_i) \
;         __builtin_amdgcn_global_load_lds((const unsigned*)((const char*)(gbase) + (voff)[_i]), (PG8_LAS unsigned*)(lds + (bufoff) + ldsw + _i * 8192), 16, 0, 0); } while (0)
; #define PG8_LDA(dst, b, h) do { _Pragma("unroll") for (int m = 0; m < 4; ++m) _Pragma("unroll") for (int k = 0; k < 2; ++k) dst[m][k] = *(const PG8_LAS bf16x8*)(lds + PG8_SA(b, h) + aoff + m * 2048 + k * 1024); } while (0)
; #define PG8_MMA(ai, bj, At, Bt) do { __builtin_amdgcn_s_setprio(1); _Pragma("unroll") for (int m = 0; m < 4; ++m) _Pragma("unroll") for (int n = 0; n < 2; ++n) _Pragma("unroll") for (int k = 0; k < 2; ++k) \
;         acc[ai][bj][m][n] = __builtin_amdgcn_mfma_f32_16x16x32_bf16(Bt[n][k], At[m][k], acc[ai][bj][m][n], 0, 0, 0); __builtin_amdgcn_s_setprio(0); } while (0)
; #define PG8_WAIT_V(n) asm volatile("s_waitcnt vmcnt(" #n ")" ::: "memory")
; #define PG8_WAIT_L(n) asm volatile("s_waitcnt lgkmcnt(" #n ")" ::: "memory")
; #define PG8_BAR __builtin_amdgcn_s_barrier()
; #define PG8_SCHED __builtin_amdgcn_sched_barrier(0)
; template <class Epi, class Sched, bool ALIGN_EPI = false, bool SP2 = false>
; __device__ __forceinline__ void gemm_phase(PG8_LAS unsigned char* lds, const Gemm g, const Sched& S, const Epi& E) {
;     ...
;             PG8_WAIT_V(8); PG8_WAIT_L(0); PG8_BAR; PG8_MMA(0, 0, At, B0); PG8_MMA(0, 1, At, B1); PG8_BAR; PG8_SCHED;
;             PG8_LDA(At, 0, 1); PG8_STAGE(PG8_SB(0, 0), b2, voffB); PG8_STAGE(PG8_SB(0, 1), b2 + hstep, voffB); PG8_STAGE(PG8_SA(0, 0), a2, voffA);
.Lrj_P6_0:
	s_waitcnt lgkmcnt(0)
	s_barrier
	s_setprio 1
	s_waitcnt lgkmcnt(0)
	v_mfma_f32_16x16x32_bf16 v[124:127], v[152:155], v[184:187], v[124:127]
	v_mfma_f32_16x16x32_bf16 v[120:123], v[160:163], v[184:187], v[120:123]
	v_mfma_f32_16x16x32_bf16 v[108:111], v[152:155], v[192:195], v[108:111]
	v_mfma_f32_16x16x32_bf16 v[104:107], v[160:163], v[192:195], v[104:107]
	v_mfma_f32_16x16x32_bf16 v[92:95], v[152:155], v[200:203], v[92:95]
	v_mfma_f32_16x16x32_bf16 v[88:91], v[160:163], v[200:203], v[88:91]
	v_mfma_f32_16x16x32_bf16 v[76:79], v[152:155], v[208:211], v[76:79]
	v_mfma_f32_16x16x32_bf16 v[72:75], v[160:163], v[208:211], v[72:75]
	v_mfma_f32_16x16x32_bf16 v[124:127], v[156:159], v[188:191], v[124:127]
	v_mfma_f32_16x16x32_bf16 v[120:123], v[164:167], v[188:191], v[120:123]
	v_mfma_f32_16x16x32_bf16 v[108:111], v[156:159], v[196:199], v[108:111]
	v_mfma_f32_16x16x32_bf16 v[104:107], v[164:167], v[196:199], v[104:107]
	v_mfma_f32_16x16x32_bf16 v[92:95], v[156:159], v[204:207], v[92:95]
	v_mfma_f32_16x16x32_bf16 v[88:91], v[164:167], v[204:207], v[88:91]
	v_mfma_f32_16x16x32_bf16 v[76:79], v[156:159], v[212:215], v[76:79]
	v_mfma_f32_16x16x32_bf16 v[72:75], v[164:167], v[212:215], v[72:75]
	v_mfma_f32_16x16x32_bf16 v[116:119], v[168:171], v[184:187], v[116:119]
	v_mfma_f32_16x16x32_bf16 v[112:115], v[176:179], v[184:187], v[112:115]
	v_mfma_f32_16x16x32_bf16 v[100:103], v[168:171], v[192:195], v[100:103]
	v_mfma_f32_16x16x32_bf16 v[96:99], v[176:179], v[192:195], v[96:99]
	v_mfma_f32_16x16x32_bf16 v[84:87], v[168:171], v[200:203], v[84:87]
	v_mfma_f32_16x16x32_bf16 v[80:83], v[176:179], v[200:203], v[80:83]
	v_mfma_f32_16x16x32_bf16 v[68:71], v[168:171], v[208:211], v[68:71]
	v_mfma_f32_16x16x32_bf16 v[64:67], v[176:179], v[208:211], v[64:67]
	v_mfma_f32_16x16x32_bf16 v[116:119], v[172:175], v[188:191], v[116:119]
	v_mfma_f32_16x16x32_bf16 v[112:115], v[180:183], v[188:191], v[112:115]
	v_mfma_f32_16x16x32_bf16 v[100:103], v[172:175], v[196:199], v[100:103]
	v_mfma_f32_16x16x32_bf16 v[96:99], v[180:183], v[196:199], v[96:99]
	v_mfma_f32_16x16x32_bf16 v[84:87], v[172:175], v[204:207], v[84:87]
	v_mfma_f32_16x16x32_bf16 v[80:83], v[180:183], v[204:207], v[80:83]
	v_mfma_f32_16x16x32_bf16 v[68:71], v[172:175], v[212:215], v[68:71]
	v_mfma_f32_16x16x32_bf16 v[64:67], v[180:183], v[212:215], v[64:67]
	s_setprio 0
	s_barrier
	s_add_i32 s69, s51, s39
	v_lshl_add_u64 v[144:145], s[30:31], 0, v[132:133]
	s_mov_b32 m0, s69
	ds_read_b128 v[184:187], v151 offset:16384
	ds_read_b128 v[188:191], v151 offset:17408
	ds_read_b128 v[192:195], v151 offset:18432
	ds_read_b128 v[196:199], v151 offset:19456
	ds_read_b128 v[200:203], v151 offset:20480
	ds_read_b128 v[204:207], v151 offset:21504
	ds_read_b128 v[208:211], v151 offset:22528
	ds_read_b128 v[212:215], v151 offset:23552
	global_load_lds_dwordx4 v[144:145], off
	s_add_i32 m0, s69, 0x2000
	s_add_u32 s70, s30, 0x100000
	v_lshl_add_u64 v[216:217], s[30:31], 0, v[128:129]
	s_addc_u32 s71, s31, 0
	s_add_i32 s69, s52, s39
	global_load_lds_dwordx4 v[216:217], off
	v_lshl_add_u64 v[218:219], s[70:71], 0, v[132:133]
	s_mov_b32 m0, s69
	v_lshl_add_u64 v[220:221], s[34:35], 0, v[130:131]
	global_load_lds_dwordx4 v[218:219], off
	v_lshl_add_u64 v[218:219], s[70:71], 0, v[128:129]
	s_add_i32 m0, s69, 0x2000
	s_nop 0
	global_load_lds_dwordx4 v[218:219], off
	v_lshl_add_u64 v[218:219], s[34:35], 0, v[134:135]
	s_mov_b32 m0, s27
	s_nop 0
	global_load_lds_dwordx4 v[218:219], off
	s_mov_b32 m0, s42
	s_nop 0
	global_load_lds_dwordx4 v[220:221], off
	s_cmp_eq_u32 s99, 1
	s_cbranch_scc1 .Lrw_P6_1
	s_waitcnt vmcnt(8)
	s_branch .Lrj_P6_1

; #define PG8_STAGE(bufoff, gbase, voff) do { _Pragma("unroll") for (int _i = 0; _i < 2; ++_i) \
;         __builtin_amdgcn_global_load_lds((const unsigned*)((const char*)(gbase) + (voff)[_i]), (PG8_LAS unsigned*)(lds + (bufoff) + ldsw + _i * 8192), 16, 0, 0); } while (0)
; #define PG8_LDA(dst, b, h) do { _Pragma("unroll") for (int m = 0; m < 4; ++m) _Pragma("unroll") for (int k = 0; k < 2; ++k) dst[m][k] = *(const PG8_LAS bf16x8*)(lds + PG8_SA(b, h) + aoff + m * 2048 + k * 1024); } while (0)
; #define PG8_LDB(dst, b, h) do { _Pragma("unroll") for (int n = 0; n < 2; ++n) _Pragma("unroll") for (int k = 0; k < 2; ++k) dst[n][k] = *(const PG8_LAS bf16x8*)(lds + PG8_SB(b, h) + boff + n * 2048 + k * 1024); } while (0)
; #define PG8_MMA(ai, bj, At, Bt) do { __builtin_amdgcn_s_setprio(1); _Pragma("unroll") for (int m = 0; m < 4; ++m) _Pragma("unroll") for (int n = 0; n < 2; ++n) _Pragma("unroll") for (int k = 0; k < 2; ++k) \
;         acc[ai][bj][m][n] = __builtin_amdgcn_mfma_f32_16x16x32_bf16(Bt[n][k], At[m][k], acc[ai][bj][m][n], 0, 0, 0); __builtin_amdgcn_s_setprio(0); } while (0)
; #define PG8_WAIT_V(n) asm volatile("s_waitcnt vmcnt(" #n ")" ::: "memory")
; #define PG8_WAIT_L(n) asm volatile("s_waitcnt lgkmcnt(" #n ")" ::: "memory")
; #define PG8_BAR __builtin_amdgcn_s_barrier()
; #define PG8_SCHED __builtin_amdgcn_sched_barrier(0)
; template <class Epi, class Sched, bool ALIGN_EPI = false, bool SP2 = false>
; __device__ __forceinline__ void gemm_phase(PG8_LAS unsigned char* lds, const Gemm g, const Sched& S, const Epi& E) {
;     ...
;             PG8_WAIT_V(8); PG8_WAIT_L(0); PG8_BAR; PG8_MMA(1, 0, At, B0); PG8_MMA(1, 1, At, B1); PG8_BAR; PG8_SCHED;
;             PG8_LDB(B0, 1, 0); PG8_LDB(B1, 1, 1); PG8_SCHED; PG8_LDA(At, 1, 0); PG8_STAGE(PG8_SA(0, 1), a2 + hstep, voffA);
;             PG8_WAIT_V(8); PG8_WAIT_L(0); PG8_BAR; PG8_MMA(0, 0, At, B0); PG8_MMA(0, 1, At, B1); PG8_BAR; PG8_SCHED;
.Lrj_P6_1:
	s_waitcnt lgkmcnt(0)
	s_barrier
	s_setprio 1
	s_waitcnt lgkmcnt(0)
	v_mfma_f32_16x16x32_bf16 v[60:63], v[152:155], v[184:187], v[60:63]
	v_mfma_f32_16x16x32_bf16 v[56:59], v[160:163], v[184:187], v[56:59]
	v_mfma_f32_16x16x32_bf16 v[44:47], v[152:155], v[192:195], v[44:47]
	v_mfma_f32_16x16x32_bf16 v[40:43], v[160:163], v[192:195], v[40:43]
	v_mfma_f32_16x16x32_bf16 v[28:31], v[152:155], v[200:203], v[28:31]
	v_mfma_f32_16x16x32_bf16 v[24:27], v[160:163], v[200:203], v[24:27]
	v_mfma_f32_16x16x32_bf16 v[12:15], v[152:155], v[208:211], v[12:15]
	v_mfma_f32_16x16x32_bf16 v[8:11], v[160:163], v[208:211], v[8:11]
	v_mfma_f32_16x16x32_bf16 v[60:63], v[156:159], v[188:191], v[60:63]
	v_mfma_f32_16x16x32_bf16 v[56:59], v[164:167], v[188:191], v[56:59]
	v_mfma_f32_16x16x32_bf16 v[44:47], v[156:159], v[196:199], v[44:47]
	v_mfma_f32_16x16x32_bf16 v[40:43], v[164:167], v[196:199], v[40:43]
	v_mfma_f32_16x16x32_bf16 v[28:31], v[156:159], v[204:207], v[28:31]
	v_mfma_f32_16x16x32_bf16 v[24:27], v[164:167], v[204:207], v[24:27]
	v_mfma_f32_16x16x32_bf16 v[12:15], v[156:159], v[212:215], v[12:15]
	v_mfma_f32_16x16x32_bf16 v[8:11], v[164:167], v[212:215], v[8:11]
	v_mfma_f32_16x16x32_bf16 v[52:55], v[168:171], v[184:187], v[52:55]
	v_mfma_f32_16x16x32_bf16 v[48:51], v[176:179], v[184:187], v[48:51]
	v_mfma_f32_16x16x32_bf16 v[36:39], v[168:171], v[192:195], v[36:39]
	v_mfma_f32_16x16x32_bf16 v[32:35], v[176:179], v[192:195], v[32:35]
	v_mfma_f32_16x16x32_bf16 v[20:23], v[168:171], v[200:203], v[20:23]
	v_mfma_f32_16x16x32_bf16 v[16:19], v[176:179], v[200:203], v[16:19]
	v_mfma_f32_16x16x32_bf16 v[4:7], v[168:171], v[208:211], v[4:7]
	v_mfma_f32_16x16x32_bf16 v[0:3], v[176:179], v[208:211], v[0:3]
	v_mfma_f32_16x16x32_bf16 v[52:55], v[172:175], v[188:191], v[52:55]
	v_mfma_f32_16x16x32_bf16 v[48:51], v[180:183], v[188:191], v[48:51]
	v_mfma_f32_16x16x32_bf16 v[36:39], v[172:175], v[196:199], v[36:39]
	v_mfma_f32_16x16x32_bf16 v[32:35], v[180:183], v[196:199], v[32:35]
	v_mfma_f32_16x16x32_bf16 v[20:23], v[172:175], v[204:207], v[20:23]
	v_mfma_f32_16x16x32_bf16 v[16:19], v[180:183], v[204:207], v[16:19]
	v_mfma_f32_16x16x32_bf16 v[4:7], v[172:175], v[212:215], v[4:7]
	v_mfma_f32_16x16x32_bf16 v[0:3], v[180:183], v[212:215], v[0:3]
	s_setprio 0
	s_barrier
	s_add_i32 s69, 0, 0x18000
	s_add_i32 s70, 0, 0x1c000
	v_add_u32_e32 v164, s69, v147
	v_add_u32_e32 v180, s70, v147
	ds_read_b128 v[152:155], v164
	ds_read_b128 v[156:159], v164 offset:1024
	ds_read_b128 v[160:163], v164 offset:2048
	ds_read_b128 v[164:167], v164 offset:3072
	ds_read_b128 v[168:171], v180
	ds_read_b128 v[172:175], v180 offset:1024
	ds_read_b128 v[176:179], v180 offset:2048
	ds_read_b128 v[180:183], v180 offset:3072
	s_add_u32 s34, s34, 0x100000
	s_addc_u32 s35, s35, 0
	s_mov_b32 m0, s43
	v_lshl_add_u64 v[222:223], s[34:35], 0, v[134:135]
	ds_read_b128 v[184:187], v151 offset:32768
	ds_read_b128 v[188:191], v151 offset:33792
	ds_read_b128 v[192:195], v151 offset:34816
	ds_read_b128 v[196:199], v151 offset:35840
	ds_read_b128 v[200:203], v151 offset:36864
	ds_read_b128 v[204:207], v151 offset:37888
	ds_read_b128 v[208:211], v151 offset:38912
	ds_read_b128 v[212:215], v151 offset:39936
	global_load_lds_dwordx4 v[222:223], off
	v_lshl_add_u64 v[222:223], s[34:35], 0, v[130:131]
	s_mov_b32 m0, s46
	s_nop 0
	global_load_lds_dwordx4 v[222:223], off
	s_waitcnt vmcnt(8)
	s_waitcnt lgkmcnt(0)
	s_barrier
	s_setprio 1
	s_waitcnt lgkmcnt(0)
	v_mfma_f32_16x16x32_bf16 v[124:127], v[152:155], v[184:187], v[124:127]
	v_mfma_f32_16x16x32_bf16 v[120:123], v[160:163], v[184:187], v[120:123]
	v_mfma_f32_16x16x32_bf16 v[108:111], v[152:155], v[192:195], v[108:111]
	v_mfma_f32_16x16x32_bf16 v[104:107], v[160:163], v[192:195], v[104:107]
	v_mfma_f32_16x16x32_bf16 v[92:95], v[152:155], v[200:203], v[92:95]
	v_mfma_f32_16x16x32_bf16 v[88:91], v[160:163], v[200:203], v[88:91]
	v_mfma_f32_16x16x32_bf16 v[76:79], v[152:155], v[208:211], v[76:79]
	v_mfma_f32_16x16x32_bf16 v[72:75], v[160:163], v[208:211], v[72:75]
	v_mfma_f32_16x16x32_bf16 v[124:127], v[156:159], v[188:191], v[124:127]
	v_mfma_f32_16x16x32_bf16 v[120:123], v[164:167], v[188:191], v[120:123]
	v_mfma_f32_16x16x32_bf16 v[108:111], v[156:159], v[196:199], v[108:111]
	v_mfma_f32_16x16x32_bf16 v[104:107], v[164:167], v[196:199], v[104:107]
	v_mfma_f32_16x16x32_bf16 v[92:95], v[156:159], v[204:207], v[92:95]
	v_mfma_f32_16x16x32_bf16 v[88:91], v[164:167], v[204:207], v[88:91]
	v_mfma_f32_16x16x32_bf16 v[76:79], v[156:159], v[212:215], v[76:79]
	v_mfma_f32_16x16x32_bf16 v[72:75], v[164:167], v[212:215], v[72:75]
	v_mfma_f32_16x16x32_bf16 v[116:119], v[168:171], v[184:187], v[116:119]
	v_mfma_f32_16x16x32_bf16 v[112:115], v[176:179], v[184:187], v[112:115]
	v_mfma_f32_16x16x32_bf16 v[100:103], v[168:171], v[192:195], v[100:103]
	v_mfma_f32_16x16x32_bf16 v[96:99], v[176:179], v[192:195], v[96:99]
	v_mfma_f32_16x16x32_bf16 v[84:87], v[168:171], v[200:203], v[84:87]
	v_mfma_f32_16x16x32_bf16 v[80:83], v[176:179], v[200:203], v[80:83]
	v_mfma_f32_16x16x32_bf16 v[68:71], v[168:171], v[208:211], v[68:71]
	v_mfma_f32_16x16x32_bf16 v[64:67], v[176:179], v[208:211], v[64:67]
	v_mfma_f32_16x16x32_bf16 v[116:119], v[172:175], v[188:191], v[116:119]
	v_mfma_f32_16x16x32_bf16 v[112:115], v[180:183], v[188:191], v[112:115]
	v_mfma_f32_16x16x32_bf16 v[100:103], v[172:175], v[196:199], v[100:103]
	v_mfma_f32_16x16x32_bf16 v[96:99], v[180:183], v[196:199], v[96:99]
	v_mfma_f32_16x16x32_bf16 v[84:87], v[172:175], v[204:207], v[84:87]
	v_mfma_f32_16x16x32_bf16 v[80:83], v[180:183], v[204:207], v[80:83]
	v_mfma_f32_16x16x32_bf16 v[68:71], v[172:175], v[212:215], v[68:71]
	v_mfma_f32_16x16x32_bf16 v[64:67], v[180:183], v[212:215], v[64:67]
	s_setprio 0
	s_barrier
; #define PG8_STAGE(bufoff, gbase, voff) do { _Pragma("unroll") for (int _i = 0; _i < 2; ++_i) \
;         __builtin_amdgcn_global_load_lds((const unsigned*)((const char*)(gbase) + (voff)[_i]), (PG8_LAS unsigned*)(lds + (bufoff) + ldsw + _i * 8192), 16, 0, 0); } while (0)
; #define PG8_LDA(dst, b, h) do { _Pragma("unroll") for (int m = 0; m < 4; ++m) _Pragma("unroll") for (int k = 0; k < 2; ++k) dst[m][k] = *(const PG8_LAS bf16x8*)(lds + PG8_SA(b, h) + aoff + m * 2048 + k * 1024); } while (0)
; #define PG8_MMA(ai, bj, At, Bt) do { __builtin_amdgcn_s_setprio(1); _Pragma("unroll") for (int m = 0; m < 4; ++m) _Pragma("unroll") for (int n = 0; n < 2; ++n) _Pragma("unroll") for (int k = 0; k < 2; ++k) \
;         acc[ai][bj][m][n] = __builtin_amdgcn_mfma_f32_16x16x32_bf16(Bt[n][k], At[m][k], acc[ai][bj][m][n], 0, 0, 0); __builtin_amdgcn_s_setprio(0); } while (0)
; #define PG8_WAIT_V(n) asm volatile("s_waitcnt vmcnt(" #n ")" ::: "memory")
; #define PG8_WAIT_L(n) asm volatile("s_waitcnt lgkmcnt(" #n ")" ::: "memory")
; #define PG8_BAR __builtin_amdgcn_s_barrier()
; #define PG8_SCHED __builtin_amdgcn_sched_barrier(0)
; template <class Epi, class Sched, bool ALIGN_EPI = false, bool SP2 = false>
; __device__ __forceinline__ void gemm_phase(PG8_LAS unsigned char* lds, const Gemm g, const Sched& S, const Epi& E) {
;     ...
;             PG8_LDA(At, 1, 1); PG8_STAGE(PG8_SB(1, 0), b3, voffB); PG8_STAGE(PG8_SB(1, 1), b3 + hstep, voffB); PG8_STAGE(PG8_SA(1, 0), a3, voffA);
;             PG8_WAIT_V(8); PG8_WAIT_L(0); PG8_BAR; PG8_MMA(1, 0, At, B0); PG8_MMA(1, 1, At, B1); PG8_BAR; PG8_SCHED;
;     __device__ __forceinline__ void operator()(const f32x4 (&acc)[2][2][4][2], const Unit& u, int wr, int wc, int fr, int fq) const {
;     ...
;             for (int m = 0; m < 4; ++m) { float* yr = y + (size_t)(rbase + ai * 128 + m * 16) * 1024 + cb;
; #pragma unroll
;                 for (int bj = 0; bj < 2; ++bj) { float* yp = yr + bj * 128; const f32x4 a = *(const f32x4*)yp + acc[ai][bj][m][0], b = *(const f32x4*)(yp + 4) + acc[ai][bj][m][1]; *(f32x4*)yp = a; *(f32x4*)(yp + 4) = b; }
	s_add_i32 s34, s69, s39
	v_lshl_add_u64 v[144:145], v[144:145], 0, s[6:7]
	s_mov_b32 m0, s34
	ds_read_b128 v[184:187], v151 offset:49152
	ds_read_b128 v[188:191], v151 offset:50176
	ds_read_b128 v[192:195], v151 offset:51200
	ds_read_b128 v[196:199], v151 offset:52224
	ds_read_b128 v[200:203], v151 offset:53248
	ds_read_b128 v[204:207], v151 offset:54272
	ds_read_b128 v[208:211], v151 offset:55296
	ds_read_b128 v[212:215], v151 offset:56320
	global_load_lds_dwordx4 v[144:145], off
	s_add_i32 m0, s34, 0x2000
	s_add_u32 s30, s30, 0x100080
	v_lshl_add_u64 v[144:145], v[216:217], 0, s[6:7]
	s_addc_u32 s31, s31, 0
	s_add_i32 s34, s70, s39
	global_load_lds_dwordx4 v[144:145], off
	v_lshl_add_u64 v[144:145], s[30:31], 0, v[132:133]
	s_mov_b32 m0, s34
	s_nop 0
	global_load_lds_dwordx4 v[144:145], off
	v_lshl_add_u64 v[144:145], s[30:31], 0, v[128:129]
	s_add_i32 m0, s34, 0x2000
	s_nop 0
	global_load_lds_dwordx4 v[144:145], off
	v_lshl_add_u64 v[144:145], v[218:219], 0, s[6:7]
	s_mov_b32 m0, s48
	s_nop 0
	global_load_lds_dwordx4 v[144:145], off
	v_lshl_add_u64 v[144:145], v[220:221], 0, s[6:7]
	s_mov_b32 m0, s49
	s_nop 0
	global_load_lds_dwordx4 v[144:145], off
	s_waitcnt vmcnt(8)
	s_waitcnt lgkmcnt(0)
	s_barrier
	s_setprio 1
	s_waitcnt lgkmcnt(0)
	v_mfma_f32_16x16x32_bf16 v[60:63], v[152:155], v[184:187], v[60:63]
	v_mfma_f32_16x16x32_bf16 v[56:59], v[160:163], v[184:187], v[56:59]
	v_mfma_f32_16x16x32_bf16 v[44:47], v[152:155], v[192:195], v[44:47]
	v_mfma_f32_16x16x32_bf16 v[40:43], v[160:163], v[192:195], v[40:43]
	v_mfma_f32_16x16x32_bf16 v[28:31], v[152:155], v[200:203], v[28:31]
	v_mfma_f32_16x16x32_bf16 v[24:27], v[160:163], v[200:203], v[24:27]
	v_mfma_f32_16x16x32_bf16 v[12:15], v[152:155], v[208:211], v[12:15]
	v_mfma_f32_16x16x32_bf16 v[8:11], v[160:163], v[208:211], v[8:11]
	v_mfma_f32_16x16x32_bf16 v[60:63], v[156:159], v[188:191], v[60:63]
	v_mfma_f32_16x16x32_bf16 v[56:59], v[164:167], v[188:191], v[56:59]
	v_mfma_f32_16x16x32_bf16 v[44:47], v[156:159], v[196:199], v[44:47]
	v_mfma_f32_16x16x32_bf16 v[40:43], v[164:167], v[196:199], v[40:43]
	v_mfma_f32_16x16x32_bf16 v[28:31], v[156:159], v[204:207], v[28:31]
	v_mfma_f32_16x16x32_bf16 v[24:27], v[164:167], v[204:207], v[24:27]
	v_mfma_f32_16x16x32_bf16 v[12:15], v[156:159], v[212:215], v[12:15]
	v_mfma_f32_16x16x32_bf16 v[8:11], v[164:167], v[212:215], v[8:11]
	v_mfma_f32_16x16x32_bf16 v[52:55], v[168:171], v[184:187], v[52:55]
	v_mfma_f32_16x16x32_bf16 v[48:51], v[176:179], v[184:187], v[48:51]
	v_mfma_f32_16x16x32_bf16 v[36:39], v[168:171], v[192:195], v[36:39]
	v_mfma_f32_16x16x32_bf16 v[32:35], v[176:179], v[192:195], v[32:35]
	v_mfma_f32_16x16x32_bf16 v[20:23], v[168:171], v[200:203], v[20:23]
	v_mfma_f32_16x16x32_bf16 v[16:19], v[176:179], v[200:203], v[16:19]
	v_mfma_f32_16x16x32_bf16 v[4:7], v[168:171], v[208:211], v[4:7]
	v_mfma_f32_16x16x32_bf16 v[0:3], v[176:179], v[208:211], v[0:3]
	v_mfma_f32_16x16x32_bf16 v[52:55], v[172:175], v[188:191], v[52:55]
	v_mfma_f32_16x16x32_bf16 v[48:51], v[180:183], v[188:191], v[48:51]
	v_mfma_f32_16x16x32_bf16 v[36:39], v[172:175], v[196:199], v[36:39]
	v_mfma_f32_16x16x32_bf16 v[32:35], v[180:183], v[196:199], v[32:35]
	v_mfma_f32_16x16x32_bf16 v[20:23], v[172:175], v[204:207], v[20:23]
	v_mfma_f32_16x16x32_bf16 v[16:19], v[180:183], v[204:207], v[16:19]
	v_mfma_f32_16x16x32_bf16 v[4:7], v[172:175], v[212:215], v[4:7]
	v_mfma_f32_16x16x32_bf16 v[0:3], v[180:183], v[212:215], v[0:3]
	s_setprio 0
	s_barrier
	s_mov_b32 s99, 0
	s_add_i32 s68, s68, 2
	s_add_u32 s28, s28, 0x100
	s_addc_u32 s29, s29, 0
	s_add_u32 s66, s66, 0x100
	s_addc_u32 s67, s67, 0
	s_cmp_gt_u32 s68, 61
	s_cbranch_scc0 .LBB0_2136
	v_and_b32_e32 v216, 0xfffffff7, v146
	v_lshl_add_u32 v216, s26, 8, v216
	v_bfe_u32 v220, v146, 3, 1
	v_lshl_add_u32 v220, v220, 2, v148
	v_lshl_or_b32 v220, s63, 8, v220
	v_ashrrev_i32_e32 v217, 31, v216
	v_ashrrev_i32_e32 v221, 31, v220
	v_lshlrev_b64 v[216:217], 12, v[216:217]
	v_lshlrev_b64 v[220:221], 2, v[220:221]
	v_lshl_add_u64 v[216:217], s[84:85], 0, v[216:217]
	v_lshl_add_u64 v[216:217], v[216:217], 0, v[220:221]
	s_mov_b64 s[98:99], 0x8000
	v_lshl_add_u64 v[218:219], v[216:217], 0, s[98:99]
	v_mov_b64_e32 v[220:221], v[216:217]
	v_mov_b64_e32 v[222:223], v[218:219]
	s_mov_b64 s[98:99], 0x10000
	s_mov_b64 s[100:101], 0x50000
	global_load_dwordx4 v[152:155], v[216:217], off
	global_load_dwordx4 v[156:159], v[218:219], off
	global_load_dwordx4 v[160:163], v[216:217], off offset:512
	global_load_dwordx4 v[164:167], v[218:219], off offset:512
	v_lshl_add_u64 v[216:217], v[216:217], 0, s[98:99]
	v_lshl_add_u64 v[218:219], v[218:219], 0, s[98:99]
	global_load_dwordx4 v[168:171], v[216:217], off
	global_load_dwordx4 v[172:175], v[218:219], off
	global_load_dwordx4 v[176:179], v[216:217], off offset:512
	global_load_dwordx4 v[180:183], v[218:219], off offset:512
	v_lshl_add_u64 v[216:217], v[216:217], 0, s[98:99]
	v_lshl_add_u64 v[218:219], v[218:219], 0, s[98:99]
	global_load_dwordx4 v[184:187], v[216:217], off
	global_load_dwordx4 v[188:191], v[218:219], off
	global_load_dwordx4 v[192:195], v[216:217], off offset:512
	global_load_dwordx4 v[196:199], v[218:219], off offset:512
	v_lshl_add_u64 v[216:217], v[216:217], 0, s[98:99]
	v_lshl_add_u64 v[218:219], v[218:219], 0, s[98:99]
	global_load_dwordx4 v[200:203], v[216:217], off
	global_load_dwordx4 v[204:207], v[218:219], off
	global_load_dwordx4 v[208:211], v[216:217], off offset:512
	global_load_dwordx4 v[212:215], v[218:219], off offset:512
	v_lshl_add_u64 v[216:217], v[216:217], 0, s[100:101]
	v_lshl_add_u64 v[218:219], v[218:219], 0, s[100:101]
	global_load_dwordx4 v[228:231], v[216:217], off
	global_load_dwordx4 v[232:235], v[218:219], off
	global_load_dwordx4 v[236:239], v[216:217], off offset:512
	global_load_dwordx4 v[240:243], v[218:219], off offset:512
	v_lshl_add_u64 v[216:217], v[216:217], 0, s[98:99]
	v_lshl_add_u64 v[218:219], v[218:219], 0, s[98:99]
	s_and_b64 vcc, exec, s[8:9]
	s_cbranch_vccz .LBB0_2139
	s_barrier
